# fill the M0 wait state: the s_nop 0 between each M0 write and its LDS-DMA replaced by one of the phase's ds_reads (10 fewer issue slots per K-iteration in the R phases)
# baseline (speedup 1.0000x reference)
; #define PG8_STAGE(bufoff, gbase, voff) do { _Pragma("unroll") for (int _i = 0; _i < 2; ++_i) \
;         __builtin_amdgcn_global_load_lds((const unsigned*)((const char*)(gbase) + (voff)[_i]), (LAS unsigned*)(lds + (bufoff) + ldsw + _i * 8192), 16, 0, 0); } while (0)
; #define PG8_LDA(dst, b, h) do { _Pragma("unroll") for (int m = 0; m < 4; ++m) _Pragma("unroll") for (int k = 0; k < 2; ++k) dst[m][k] = *(const LAS bf16x8*)(lds + PG8_SA(b, h) + aoff + m * 2048 + k * 1024); } while (0)
; #define PG8_LDB(dst, b, h) do { _Pragma("unroll") for (int n = 0; n < 2; ++n) _Pragma("unroll") for (int k = 0; k < 2; ++k) dst[n][k] = *(const LAS bf16x8*)(lds + PG8_SB(b, h) + boff + n * 2048 + k * 1024); } while (0)
; #define PG8_MMA(ai, bj, At, Bt) do { __builtin_amdgcn_s_setprio(3); _Pragma("unroll") for (int m = 0; m < 4; ++m) _Pragma("unroll") for (int n = 0; n < 2; ++n) _Pragma("unroll") for (int k = 0; k < 2; ++k) \
;         acc[ai][bj][m][n] = __builtin_amdgcn_mfma_f32_16x16x32_bf16(Bt[n][k], At[m][k], acc[ai][bj][m][n], 0, 0, 0); __builtin_amdgcn_s_setprio(0); } while (0)
; #define PG8_WAIT_V(n) asm volatile("s_waitcnt vmcnt(" #n ")" ::: "memory")
; #define PG8_WAIT_L(n) asm volatile("s_waitcnt lgkmcnt(" #n ")" ::: "memory")
; #define PG8_BAR __builtin_amdgcn_s_barrier()
; #define PG8_SCHED __builtin_amdgcn_sched_barrier(0)
; template <class Epi, class Sched, bool ALIGN_EPI = false, bool SP2 = false>
; __device__ __forceinline__ void gemm_phase(LAS unsigned char* lds, const Gemm g, const Sched& S, const Epi& E) {
;     ...
;             PG8_LDB(B0, 0, 0); PG8_LDB(B1, 0, 1); PG8_SCHED; PG8_LDA(At, 0, 0); PG8_STAGE(PG8_SA(1, 1), a1 + hsA, voffA);
;             PG8_WAIT_V(8); PG8_WAIT_L(0); PG8_BAR; PG8_MMA(0, 0, At, B0); PG8_MMA(0, 1, At, B1); PG8_BAR; PG8_SCHED;
;             PG8_LDA(At, 0, 1); PG8_STAGE(PG8_SB(0, 0), b2, voffB); PG8_STAGE(PG8_SB(0, 1), b2 + hsB, voffB); PG8_STAGE(PG8_SA(0, 0), a2, voffA);
;             PG8_WAIT_V(8); PG8_WAIT_L(0); PG8_BAR; PG8_MMA(1, 0, At, B0); PG8_MMA(1, 1, At, B1); PG8_BAR; PG8_SCHED;
.LBB0_64:
	ds_read_b128 v[128:131], v158
	ds_read_b128 v[150:153], v251
	ds_read_b128 v[166:169], v158 offset:2048
	ds_read_b128 v[170:173], v251 offset:2048
	ds_read_b128 v[174:177], v159
	ds_read_b128 v[178:181], v252
	ds_read_b128 v[182:185], v159 offset:2048
	ds_read_b128 v[186:189], v252 offset:2048
	s_add_u32 s6, s4, 0xffefc080
	s_addc_u32 s7, s5, -1
	s_cmp_eq_u32 s91, 60
	s_cselect_b32 s63, s59, s7
	s_cselect_b32 s62, s58, s6
	s_cselect_b32 s7, s61, s90
	s_cselect_b32 s6, s60, s89
	s_sub_u32 s100, s4, 0x104000
	s_subb_u32 s101, s5, 0
	s_mov_b32 m0, s76
	ds_read_b128 v[214:217], v250 offset:4096
	global_load_lds_dwordx4 v132, s[100:101]
	s_mov_b32 m0, s77
	ds_read_b128 v[218:221], v160 offset:6144
	global_load_lds_dwordx4 v136, s[100:101]
	s_add_i32 m0, s68, 0xc000
	ds_read_b128 v[190:193], v160
	ds_read_b128 v[194:197], v250
	ds_read_b128 v[198:201], v160 offset:2048
	ds_read_b128 v[206:209], v250 offset:2048
	ds_read_b128 v[210:213], v160 offset:4096
	global_load_lds_dwordx4 v142, s[4:5]
	s_add_i32 m0, s68, 0xe000
	ds_read_b128 v[222:225], v250 offset:6144
	global_load_lds_dwordx4 v144, s[4:5]
	s_waitcnt vmcnt(8)
	s_waitcnt lgkmcnt(0)
	s_setprio 2
	s_barrier
	v_mfma_f32_16x16x32_bf16 v[124:127], v[128:131], v[190:193], v[124:127]
	v_mfma_f32_16x16x32_bf16 v[124:127], v[150:153], v[194:197], v[124:127]
	v_mfma_f32_16x16x32_bf16 v[120:123], v[166:169], v[190:193], v[120:123]
	v_mfma_f32_16x16x32_bf16 v[120:123], v[170:173], v[194:197], v[120:123]
	v_mfma_f32_16x16x32_bf16 v[108:111], v[128:131], v[198:201], v[108:111]
	v_mfma_f32_16x16x32_bf16 v[108:111], v[150:153], v[206:209], v[108:111]
	v_mfma_f32_16x16x32_bf16 v[104:107], v[166:169], v[198:201], v[104:107]
	v_mfma_f32_16x16x32_bf16 v[104:107], v[170:173], v[206:209], v[104:107]
	v_mfma_f32_16x16x32_bf16 v[92:95], v[128:131], v[210:213], v[92:95]
	v_mfma_f32_16x16x32_bf16 v[92:95], v[150:153], v[214:217], v[92:95]
	v_mfma_f32_16x16x32_bf16 v[88:91], v[166:169], v[210:213], v[88:91]
	v_mfma_f32_16x16x32_bf16 v[88:91], v[170:173], v[214:217], v[88:91]
	v_mfma_f32_16x16x32_bf16 v[76:79], v[128:131], v[218:221], v[76:79]
	v_mfma_f32_16x16x32_bf16 v[76:79], v[150:153], v[222:225], v[76:79]
	v_mfma_f32_16x16x32_bf16 v[72:75], v[166:169], v[218:221], v[72:75]
	v_mfma_f32_16x16x32_bf16 v[72:75], v[170:173], v[222:225], v[72:75]
	s_setprio 0
	s_setprio 2
	v_mfma_f32_16x16x32_bf16 v[116:119], v[174:177], v[190:193], v[116:119]
	v_mfma_f32_16x16x32_bf16 v[116:119], v[178:181], v[194:197], v[116:119]
	v_mfma_f32_16x16x32_bf16 v[112:115], v[182:185], v[190:193], v[112:115]
	v_mfma_f32_16x16x32_bf16 v[112:115], v[186:189], v[194:197], v[112:115]
	v_mfma_f32_16x16x32_bf16 v[100:103], v[174:177], v[198:201], v[100:103]
	v_mfma_f32_16x16x32_bf16 v[100:103], v[178:181], v[206:209], v[100:103]
	v_mfma_f32_16x16x32_bf16 v[96:99], v[182:185], v[198:201], v[96:99]
	v_mfma_f32_16x16x32_bf16 v[96:99], v[186:189], v[206:209], v[96:99]
	v_mfma_f32_16x16x32_bf16 v[84:87], v[174:177], v[210:213], v[84:87]
	v_mfma_f32_16x16x32_bf16 v[84:87], v[178:181], v[214:217], v[84:87]
	v_mfma_f32_16x16x32_bf16 v[80:83], v[182:185], v[210:213], v[80:83]
	v_mfma_f32_16x16x32_bf16 v[80:83], v[186:189], v[214:217], v[80:83]
	v_mfma_f32_16x16x32_bf16 v[68:71], v[174:177], v[218:221], v[68:71]
	v_mfma_f32_16x16x32_bf16 v[68:71], v[178:181], v[222:225], v[68:71]
	v_mfma_f32_16x16x32_bf16 v[64:67], v[182:185], v[218:221], v[64:67]
	s_setprio 3
	s_barrier
	v_mfma_f32_16x16x32_bf16 v[64:67], v[186:189], v[222:225], v[64:67]
	s_setprio 0
	s_add_i32 s92, s82, s67
	s_mov_b32 m0, s92
	ds_read_b128 v[190:193], v160 offset:16384
	ds_read_b128 v[194:197], v250 offset:16384
	ds_read_b128 v[198:201], v160 offset:18432
	ds_read_b128 v[206:209], v250 offset:18432
	ds_read_b128 v[210:213], v160 offset:20480
	ds_read_b128 v[214:217], v250 offset:20480
	global_load_lds_dwordx4 v134, s[6:7]
	s_add_i32 m0, s92, 0x2000
	s_add_u32 s92, s6, 0x41000
	s_addc_u32 s93, s7, 0
	s_add_i32 s94, s83, s67
	global_load_lds_dwordx4 v138, s[6:7]
	s_mov_b32 m0, s94
	ds_read_b128 v[218:221], v160 offset:22528
	global_load_lds_dwordx4 v134, s[92:93]
	s_add_i32 m0, s94, 0x2000
	ds_read_b128 v[222:225], v250 offset:22528
	global_load_lds_dwordx4 v138, s[92:93]
	s_waitcnt vmcnt(6)
	s_waitcnt lgkmcnt(0)
	s_setprio 2
	s_barrier
	v_mfma_f32_16x16x32_bf16 v[60:63], v[128:131], v[190:193], v[60:63]
	v_mfma_f32_16x16x32_bf16 v[60:63], v[150:153], v[194:197], v[60:63]
	v_mfma_f32_16x16x32_bf16 v[56:59], v[166:169], v[190:193], v[56:59]
	v_mfma_f32_16x16x32_bf16 v[56:59], v[170:173], v[194:197], v[56:59]
	v_mfma_f32_16x16x32_bf16 v[44:47], v[128:131], v[198:201], v[44:47]
	v_mfma_f32_16x16x32_bf16 v[44:47], v[150:153], v[206:209], v[44:47]
	v_mfma_f32_16x16x32_bf16 v[40:43], v[166:169], v[198:201], v[40:43]
	v_mfma_f32_16x16x32_bf16 v[40:43], v[170:173], v[206:209], v[40:43]
	v_mfma_f32_16x16x32_bf16 v[28:31], v[128:131], v[210:213], v[28:31]
	v_mfma_f32_16x16x32_bf16 v[28:31], v[150:153], v[214:217], v[28:31]
	v_mfma_f32_16x16x32_bf16 v[24:27], v[166:169], v[210:213], v[24:27]
	v_mfma_f32_16x16x32_bf16 v[24:27], v[170:173], v[214:217], v[24:27]
	v_mfma_f32_16x16x32_bf16 v[12:15], v[128:131], v[218:221], v[12:15]
	v_mfma_f32_16x16x32_bf16 v[12:15], v[150:153], v[222:225], v[12:15]
	v_mfma_f32_16x16x32_bf16 v[8:11], v[166:169], v[218:221], v[8:11]
	v_mfma_f32_16x16x32_bf16 v[8:11], v[170:173], v[222:225], v[8:11]
	s_setprio 0
	s_setprio 2
	v_mfma_f32_16x16x32_bf16 v[52:55], v[174:177], v[190:193], v[52:55]
	v_mfma_f32_16x16x32_bf16 v[52:55], v[178:181], v[194:197], v[52:55]
	v_mfma_f32_16x16x32_bf16 v[48:51], v[182:185], v[190:193], v[48:51]
	v_mfma_f32_16x16x32_bf16 v[48:51], v[186:189], v[194:197], v[48:51]
	v_mfma_f32_16x16x32_bf16 v[36:39], v[174:177], v[198:201], v[36:39]
	v_mfma_f32_16x16x32_bf16 v[36:39], v[178:181], v[206:209], v[36:39]
	v_mfma_f32_16x16x32_bf16 v[32:35], v[182:185], v[198:201], v[32:35]
	v_mfma_f32_16x16x32_bf16 v[32:35], v[186:189], v[206:209], v[32:35]
	v_mfma_f32_16x16x32_bf16 v[20:23], v[174:177], v[210:213], v[20:23]
	v_mfma_f32_16x16x32_bf16 v[20:23], v[178:181], v[214:217], v[20:23]
	v_mfma_f32_16x16x32_bf16 v[16:19], v[182:185], v[210:213], v[16:19]
	v_mfma_f32_16x16x32_bf16 v[16:19], v[186:189], v[214:217], v[16:19]
	v_mfma_f32_16x16x32_bf16 v[4:7], v[174:177], v[218:221], v[4:7]
	v_mfma_f32_16x16x32_bf16 v[4:7], v[178:181], v[222:225], v[4:7]
	v_mfma_f32_16x16x32_bf16 v[0:3], v[182:185], v[218:221], v[0:3]
	s_setprio 3
	s_barrier
; #define PG8_STAGE(bufoff, gbase, voff) do { _Pragma("unroll") for (int _i = 0; _i < 2; ++_i) \
;         __builtin_amdgcn_global_load_lds((const unsigned*)((const char*)(gbase) + (voff)[_i]), (LAS unsigned*)(lds + (bufoff) + ldsw + _i * 8192), 16, 0, 0); } while (0)
; #define PG8_LDA(dst, b, h) do { _Pragma("unroll") for (int m = 0; m < 4; ++m) _Pragma("unroll") for (int k = 0; k < 2; ++k) dst[m][k] = *(const LAS bf16x8*)(lds + PG8_SA(b, h) + aoff + m * 2048 + k * 1024); } while (0)
; #define PG8_LDB(dst, b, h) do { _Pragma("unroll") for (int n = 0; n < 2; ++n) _Pragma("unroll") for (int k = 0; k < 2; ++k) dst[n][k] = *(const LAS bf16x8*)(lds + PG8_SB(b, h) + boff + n * 2048 + k * 1024); } while (0)
; #define PG8_MMA(ai, bj, At, Bt) do { __builtin_amdgcn_s_setprio(3); _Pragma("unroll") for (int m = 0; m < 4; ++m) _Pragma("unroll") for (int n = 0; n < 2; ++n) _Pragma("unroll") for (int k = 0; k < 2; ++k) \
;         acc[ai][bj][m][n] = __builtin_amdgcn_mfma_f32_16x16x32_bf16(Bt[n][k], At[m][k], acc[ai][bj][m][n], 0, 0, 0); __builtin_amdgcn_s_setprio(0); } while (0)
; #define PG8_WAIT_V(n) asm volatile("s_waitcnt vmcnt(" #n ")" ::: "memory")
; #define PG8_WAIT_L(n) asm volatile("s_waitcnt lgkmcnt(" #n ")" ::: "memory")
; #define PG8_BAR __builtin_amdgcn_s_barrier()
; #define PG8_SCHED __builtin_amdgcn_sched_barrier(0)
; template <class Epi, class Sched, bool ALIGN_EPI = false, bool SP2 = false>
; __device__ __forceinline__ void gemm_phase(LAS unsigned char* lds, const Gemm g, const Sched& S, const Epi& E) {
;     ...
;             PG8_LDB(B0, 1, 0); PG8_LDB(B1, 1, 1); PG8_SCHED; PG8_LDA(At, 1, 0); PG8_STAGE(PG8_SA(0, 1), a2 + hsA, voffA);
;             PG8_WAIT_V(8); PG8_WAIT_L(0); PG8_BAR; PG8_MMA(0, 0, At, B0); PG8_MMA(0, 1, At, B1); PG8_BAR; PG8_SCHED;
;             PG8_LDA(At, 1, 1); PG8_STAGE(PG8_SB(1, 0), b3, voffB); PG8_STAGE(PG8_SB(1, 1), b3 + hsB, voffB); PG8_STAGE(PG8_SA(1, 0), a3, voffA);
;             PG8_WAIT_V(8); PG8_WAIT_L(0); PG8_BAR; PG8_MMA(1, 0, At, B0); PG8_MMA(1, 1, At, B1); PG8_BAR; PG8_SCHED;
	v_mfma_f32_16x16x32_bf16 v[0:3], v[186:189], v[222:225], v[0:3]
	s_setprio 0
	s_add_i32 s92, 0, 0x18000
	s_add_i32 s93, 0, 0x1c000
	ds_read_b128 v[128:131], v246
	ds_read_b128 v[150:153], v247
	ds_read_b128 v[166:169], v246 offset:2048
	ds_read_b128 v[170:173], v247 offset:2048
	ds_read_b128 v[174:177], v248
	ds_read_b128 v[178:181], v249
	ds_read_b128 v[182:185], v248 offset:2048
	ds_read_b128 v[186:189], v249 offset:2048
	s_mov_b32 m0, s68
	ds_read_b128 v[214:217], v250 offset:36864
	global_load_lds_dwordx4 v132, s[62:63]
	s_mov_b32 m0, s69
	ds_read_b128 v[218:221], v160 offset:38912
	global_load_lds_dwordx4 v136, s[62:63]
	s_add_u32 s62, s62, 0x104000
	s_addc_u32 s63, s63, 0
	s_mov_b32 m0, s70
	ds_read_b128 v[190:193], v160 offset:32768
	ds_read_b128 v[194:197], v250 offset:32768
	ds_read_b128 v[198:201], v160 offset:34816
	ds_read_b128 v[206:209], v250 offset:34816
	ds_read_b128 v[210:213], v160 offset:36864
	global_load_lds_dwordx4 v132, s[62:63]
	s_mov_b32 m0, s71
	ds_read_b128 v[222:225], v250 offset:38912
	global_load_lds_dwordx4 v136, s[62:63]
	s_waitcnt vmcnt(8)
	s_waitcnt lgkmcnt(0)
	s_setprio 2
	s_barrier
	v_mfma_f32_16x16x32_bf16 v[124:127], v[128:131], v[190:193], v[124:127]
	v_mfma_f32_16x16x32_bf16 v[124:127], v[150:153], v[194:197], v[124:127]
	v_mfma_f32_16x16x32_bf16 v[120:123], v[166:169], v[190:193], v[120:123]
	v_mfma_f32_16x16x32_bf16 v[120:123], v[170:173], v[194:197], v[120:123]
	v_mfma_f32_16x16x32_bf16 v[108:111], v[128:131], v[198:201], v[108:111]
	v_mfma_f32_16x16x32_bf16 v[108:111], v[150:153], v[206:209], v[108:111]
	v_mfma_f32_16x16x32_bf16 v[104:107], v[166:169], v[198:201], v[104:107]
	v_mfma_f32_16x16x32_bf16 v[104:107], v[170:173], v[206:209], v[104:107]
	v_mfma_f32_16x16x32_bf16 v[92:95], v[128:131], v[210:213], v[92:95]
	v_mfma_f32_16x16x32_bf16 v[92:95], v[150:153], v[214:217], v[92:95]
	v_mfma_f32_16x16x32_bf16 v[88:91], v[166:169], v[210:213], v[88:91]
	v_mfma_f32_16x16x32_bf16 v[88:91], v[170:173], v[214:217], v[88:91]
	v_mfma_f32_16x16x32_bf16 v[76:79], v[128:131], v[218:221], v[76:79]
	v_mfma_f32_16x16x32_bf16 v[76:79], v[150:153], v[222:225], v[76:79]
	v_mfma_f32_16x16x32_bf16 v[72:75], v[166:169], v[218:221], v[72:75]
	v_mfma_f32_16x16x32_bf16 v[72:75], v[170:173], v[222:225], v[72:75]
	s_setprio 0
	s_setprio 2
	v_mfma_f32_16x16x32_bf16 v[116:119], v[174:177], v[190:193], v[116:119]
	v_mfma_f32_16x16x32_bf16 v[116:119], v[178:181], v[194:197], v[116:119]
	v_mfma_f32_16x16x32_bf16 v[112:115], v[182:185], v[190:193], v[112:115]
	v_mfma_f32_16x16x32_bf16 v[112:115], v[186:189], v[194:197], v[112:115]
	v_mfma_f32_16x16x32_bf16 v[100:103], v[174:177], v[198:201], v[100:103]
	v_mfma_f32_16x16x32_bf16 v[100:103], v[178:181], v[206:209], v[100:103]
	v_mfma_f32_16x16x32_bf16 v[96:99], v[182:185], v[198:201], v[96:99]
	v_mfma_f32_16x16x32_bf16 v[96:99], v[186:189], v[206:209], v[96:99]
	v_mfma_f32_16x16x32_bf16 v[84:87], v[174:177], v[210:213], v[84:87]
	v_mfma_f32_16x16x32_bf16 v[84:87], v[178:181], v[214:217], v[84:87]
	v_mfma_f32_16x16x32_bf16 v[80:83], v[182:185], v[210:213], v[80:83]
	v_mfma_f32_16x16x32_bf16 v[80:83], v[186:189], v[214:217], v[80:83]
	v_mfma_f32_16x16x32_bf16 v[68:71], v[174:177], v[218:221], v[68:71]
	v_mfma_f32_16x16x32_bf16 v[68:71], v[178:181], v[222:225], v[68:71]
	v_mfma_f32_16x16x32_bf16 v[64:67], v[182:185], v[218:221], v[64:67]
	s_setprio 3
	s_barrier
	v_mfma_f32_16x16x32_bf16 v[64:67], v[186:189], v[222:225], v[64:67]
	s_setprio 0
	s_add_i32 s62, s92, s67
	s_add_u32 s100, s6, s46
	s_addc_u32 s101, s7, s47
	s_mov_b32 m0, s62
	ds_read_b128 v[190:193], v160 offset:49152
	ds_read_b128 v[194:197], v250 offset:49152
	ds_read_b128 v[198:201], v160 offset:51200
	ds_read_b128 v[206:209], v250 offset:51200
	ds_read_b128 v[210:213], v160 offset:53248
	ds_read_b128 v[214:217], v250 offset:53248
	global_load_lds_dwordx4 v134, s[100:101]
	s_add_i32 m0, s62, 0x2000
	s_add_u32 s6, s6, 0x41080
	s_addc_u32 s7, s7, 0
	s_add_i32 s62, s93, s67
	global_load_lds_dwordx4 v138, s[100:101]
	s_mov_b32 m0, s62
	ds_read_b128 v[218:221], v160 offset:55296
	global_load_lds_dwordx4 v134, s[6:7]
	s_add_i32 m0, s62, 0x2000
	ds_read_b128 v[222:225], v250 offset:55296
	global_load_lds_dwordx4 v138, s[6:7]
	s_waitcnt vmcnt(6)
	s_waitcnt lgkmcnt(0)
	s_setprio 2
	s_barrier
	v_mfma_f32_16x16x32_bf16 v[60:63], v[128:131], v[190:193], v[60:63]
	v_mfma_f32_16x16x32_bf16 v[60:63], v[150:153], v[194:197], v[60:63]
	v_mfma_f32_16x16x32_bf16 v[56:59], v[166:169], v[190:193], v[56:59]
	v_mfma_f32_16x16x32_bf16 v[56:59], v[170:173], v[194:197], v[56:59]
	v_mfma_f32_16x16x32_bf16 v[44:47], v[128:131], v[198:201], v[44:47]
	v_mfma_f32_16x16x32_bf16 v[44:47], v[150:153], v[206:209], v[44:47]
	v_mfma_f32_16x16x32_bf16 v[40:43], v[166:169], v[198:201], v[40:43]
	v_mfma_f32_16x16x32_bf16 v[40:43], v[170:173], v[206:209], v[40:43]
	v_mfma_f32_16x16x32_bf16 v[28:31], v[128:131], v[210:213], v[28:31]
	v_mfma_f32_16x16x32_bf16 v[28:31], v[150:153], v[214:217], v[28:31]
	v_mfma_f32_16x16x32_bf16 v[24:27], v[166:169], v[210:213], v[24:27]
	v_mfma_f32_16x16x32_bf16 v[24:27], v[170:173], v[214:217], v[24:27]
	v_mfma_f32_16x16x32_bf16 v[12:15], v[128:131], v[218:221], v[12:15]
	v_mfma_f32_16x16x32_bf16 v[12:15], v[150:153], v[222:225], v[12:15]
	v_mfma_f32_16x16x32_bf16 v[8:11], v[166:169], v[218:221], v[8:11]
	v_mfma_f32_16x16x32_bf16 v[8:11], v[170:173], v[222:225], v[8:11]
	s_setprio 0
	s_setprio 2
	v_mfma_f32_16x16x32_bf16 v[52:55], v[174:177], v[190:193], v[52:55]
	v_mfma_f32_16x16x32_bf16 v[52:55], v[178:181], v[194:197], v[52:55]
	v_mfma_f32_16x16x32_bf16 v[48:51], v[182:185], v[190:193], v[48:51]
	v_mfma_f32_16x16x32_bf16 v[48:51], v[186:189], v[194:197], v[48:51]
	v_mfma_f32_16x16x32_bf16 v[36:39], v[174:177], v[198:201], v[36:39]
	v_mfma_f32_16x16x32_bf16 v[36:39], v[178:181], v[206:209], v[36:39]
	v_mfma_f32_16x16x32_bf16 v[32:35], v[182:185], v[198:201], v[32:35]
	v_mfma_f32_16x16x32_bf16 v[32:35], v[186:189], v[206:209], v[32:35]
	v_mfma_f32_16x16x32_bf16 v[20:23], v[174:177], v[210:213], v[20:23]
	v_mfma_f32_16x16x32_bf16 v[20:23], v[178:181], v[214:217], v[20:23]
	v_mfma_f32_16x16x32_bf16 v[16:19], v[182:185], v[210:213], v[16:19]
	v_mfma_f32_16x16x32_bf16 v[16:19], v[186:189], v[214:217], v[16:19]
	v_mfma_f32_16x16x32_bf16 v[4:7], v[174:177], v[218:221], v[4:7]
	v_mfma_f32_16x16x32_bf16 v[4:7], v[178:181], v[222:225], v[4:7]
	v_mfma_f32_16x16x32_bf16 v[0:3], v[182:185], v[218:221], v[0:3]
	s_setprio 3
	s_barrier
	v_mfma_f32_16x16x32_bf16 v[0:3], v[186:189], v[222:225], v[0:3]
	s_setprio 0
	s_add_i32 s91, s91, 2
	s_add_u32 s4, s4, 0x100
	s_addc_u32 s5, s5, 0
	s_add_u32 s89, s89, 0x100
	s_addc_u32 s90, s90, 0
	s_cmp_gt_u32 s91, 61
	s_cbranch_scc0 .LBB0_64
	s_and_b64 vcc, exec, s[50:51]
	s_cbranch_vccz .LBB0_67
	s_barrier

; #define PG8_STAGE(bufoff, gbase, voff) do { _Pragma("unroll") for (int _i = 0; _i < 2; ++_i) \
;         __builtin_amdgcn_global_load_lds((const unsigned*)((const char*)(gbase) + (voff)[_i]), (LAS unsigned*)(lds + (bufoff) + ldsw + _i * 8192), 16, 0, 0); } while (0)
; #define PG8_LDA(dst, b, h) do { _Pragma("unroll") for (int m = 0; m < 4; ++m) _Pragma("unroll") for (int k = 0; k < 2; ++k) dst[m][k] = *(const LAS bf16x8*)(lds + PG8_SA(b, h) + aoff + m * 2048 + k * 1024); } while (0)
; #define PG8_LDB(dst, b, h) do { _Pragma("unroll") for (int n = 0; n < 2; ++n) _Pragma("unroll") for (int k = 0; k < 2; ++k) dst[n][k] = *(const LAS bf16x8*)(lds + PG8_SB(b, h) + boff + n * 2048 + k * 1024); } while (0)
; #define PG8_MMA(ai, bj, At, Bt) do { __builtin_amdgcn_s_setprio(3); _Pragma("unroll") for (int m = 0; m < 4; ++m) _Pragma("unroll") for (int n = 0; n < 2; ++n) _Pragma("unroll") for (int k = 0; k < 2; ++k) \
;         acc[ai][bj][m][n] = __builtin_amdgcn_mfma_f32_16x16x32_bf16(Bt[n][k], At[m][k], acc[ai][bj][m][n], 0, 0, 0); __builtin_amdgcn_s_setprio(0); } while (0)
; #define PG8_WAIT_V(n) asm volatile("s_waitcnt vmcnt(" #n ")" ::: "memory")
; #define PG8_WAIT_L(n) asm volatile("s_waitcnt lgkmcnt(" #n ")" ::: "memory")
; #define PG8_BAR __builtin_amdgcn_s_barrier()
; #define PG8_SCHED __builtin_amdgcn_sched_barrier(0)
; template <class Epi, class Sched, bool ALIGN_EPI = false, bool SP2 = false>
; __device__ __forceinline__ void gemm_phase(LAS unsigned char* lds, const Gemm g, const Sched& S, const Epi& E) {
;     ...
;             PG8_LDB(B0, 0, 0); PG8_LDB(B1, 0, 1); PG8_SCHED; PG8_LDA(At, 0, 0); PG8_STAGE(PG8_SA(1, 1), a1 + hsA, voffA);
;             PG8_WAIT_V(8); PG8_WAIT_L(0); PG8_BAR; PG8_MMA(0, 0, At, B0); PG8_MMA(0, 1, At, B1); PG8_BAR; PG8_SCHED;
;             PG8_LDA(At, 0, 1); PG8_STAGE(PG8_SB(0, 0), b2, voffB); PG8_STAGE(PG8_SB(0, 1), b2 + hsB, voffB); PG8_STAGE(PG8_SA(0, 0), a2, voffA);
;             PG8_WAIT_V(8); PG8_WAIT_L(0); PG8_BAR; PG8_MMA(1, 0, At, B0); PG8_MMA(1, 1, At, B1); PG8_BAR; PG8_SCHED;
.LBB0_234:
	v_add_u32_e32 v1, s88, v194
	v_xor_b32_e32 v253, 64, v1
	ds_read_b128 v[84:87], v1
	ds_read_b128 v[96:99], v253
	ds_read_b128 v[140:143], v1 offset:2048
	ds_read_b128 v[144:147], v253 offset:2048
	v_add_u32_e32 v1, s89, v194
	v_xor_b32_e32 v253, 64, v1
	s_add_u32 s4, s64, s66
	ds_read_b128 v[152:155], v1
	ds_read_b128 v[156:159], v253
	ds_read_b128 v[160:163], v1 offset:2048
	ds_read_b128 v[182:185], v253 offset:2048
	s_addc_u32 s5, s65, s67
	s_add_u32 s4, s4, 0x100
	s_addc_u32 s5, s5, 0
	s_add_u32 s96, s93, s66
	s_addc_u32 s97, s94, s67
	s_cmpk_eq_i32 s66, 0x1f00
	s_cselect_b32 s9, s59, s5
	s_cselect_b32 s8, s91, s4
	s_cselect_b32 s5, s61, s97
	s_cselect_b32 s4, s60, s96
	s_sub_u32 s100, s66, 0x100000
	s_subb_u32 s101, s67, 0
	v_lshl_add_u64 v[242:243], v[148:149], 0, s[100:101]
	s_mov_b32 m0, s81
	v_lshl_add_u64 v[244:245], v[150:151], 0, s[100:101]
	global_load_lds_dwordx4 v[242:243], off
	s_mov_b32 m0, s82
	ds_read_b128 v[228:231], v198 offset:6144
	global_load_lds_dwordx4 v[244:245], off
	v_lshl_add_u64 v[2:3], v[148:149], 0, s[66:67]
	s_add_i32 m0, s41, 0xc000
	ds_read_b128 v[186:189], v198
	ds_read_b128 v[208:211], v250
	ds_read_b128 v[212:215], v198 offset:2048
	ds_read_b128 v[216:219], v250 offset:2048
	ds_read_b128 v[220:223], v198 offset:4096
	ds_read_b128 v[224:227], v250 offset:4096
	global_load_lds_dwordx4 v[2:3], off
	v_lshl_add_u64 v[2:3], v[150:151], 0, s[66:67]
	s_add_i32 m0, s41, 0xe000
	ds_read_b128 v[232:235], v250 offset:6144
	global_load_lds_dwordx4 v[2:3], off
	s_waitcnt vmcnt(8)
	s_waitcnt lgkmcnt(0)
	s_setprio 2
	s_barrier
	v_mfma_f32_16x16x32_bf16 v[136:139], v[84:87], v[186:189], v[136:139]
	v_mfma_f32_16x16x32_bf16 v[136:139], v[96:99], v[208:211], v[136:139]
	v_mfma_f32_16x16x32_bf16 v[132:135], v[140:143], v[186:189], v[132:135]
	v_mfma_f32_16x16x32_bf16 v[132:135], v[144:147], v[208:211], v[132:135]
	v_mfma_f32_16x16x32_bf16 v[120:123], v[84:87], v[212:215], v[120:123]
	v_mfma_f32_16x16x32_bf16 v[120:123], v[96:99], v[216:219], v[120:123]
	v_mfma_f32_16x16x32_bf16 v[116:119], v[140:143], v[212:215], v[116:119]
	v_mfma_f32_16x16x32_bf16 v[116:119], v[144:147], v[216:219], v[116:119]
	v_mfma_f32_16x16x32_bf16 v[104:107], v[84:87], v[220:223], v[104:107]
	v_mfma_f32_16x16x32_bf16 v[104:107], v[96:99], v[224:227], v[104:107]
	v_mfma_f32_16x16x32_bf16 v[100:103], v[140:143], v[220:223], v[100:103]
	v_mfma_f32_16x16x32_bf16 v[100:103], v[144:147], v[224:227], v[100:103]
	v_mfma_f32_16x16x32_bf16 v[80:83], v[84:87], v[228:231], v[80:83]
	v_mfma_f32_16x16x32_bf16 v[80:83], v[96:99], v[232:235], v[80:83]
	v_mfma_f32_16x16x32_bf16 v[76:79], v[140:143], v[228:231], v[76:79]
	v_mfma_f32_16x16x32_bf16 v[76:79], v[144:147], v[232:235], v[76:79]
	s_setprio 0
	s_setprio 2
	v_mfma_f32_16x16x32_bf16 v[128:131], v[152:155], v[186:189], v[128:131]
	v_mfma_f32_16x16x32_bf16 v[128:131], v[156:159], v[208:211], v[128:131]
	v_mfma_f32_16x16x32_bf16 v[124:127], v[160:163], v[186:189], v[124:127]
	v_mfma_f32_16x16x32_bf16 v[124:127], v[182:185], v[208:211], v[124:127]
	v_mfma_f32_16x16x32_bf16 v[112:115], v[152:155], v[212:215], v[112:115]
	v_mfma_f32_16x16x32_bf16 v[112:115], v[156:159], v[216:219], v[112:115]
	v_mfma_f32_16x16x32_bf16 v[108:111], v[160:163], v[212:215], v[108:111]
	v_mfma_f32_16x16x32_bf16 v[108:111], v[182:185], v[216:219], v[108:111]
	v_mfma_f32_16x16x32_bf16 v[92:95], v[152:155], v[220:223], v[92:95]
	v_mfma_f32_16x16x32_bf16 v[92:95], v[156:159], v[224:227], v[92:95]
	v_mfma_f32_16x16x32_bf16 v[88:91], v[160:163], v[220:223], v[88:91]
	v_mfma_f32_16x16x32_bf16 v[88:91], v[182:185], v[224:227], v[88:91]
	v_mfma_f32_16x16x32_bf16 v[72:75], v[152:155], v[228:231], v[72:75]
	v_mfma_f32_16x16x32_bf16 v[72:75], v[156:159], v[232:235], v[72:75]
	v_mfma_f32_16x16x32_bf16 v[68:71], v[160:163], v[228:231], v[68:71]
	s_setprio 3
	s_barrier
	v_mfma_f32_16x16x32_bf16 v[68:71], v[182:185], v[232:235], v[68:71]
	s_setprio 0
	s_add_i32 s96, s88, s31
	s_mov_b32 m0, s96
	ds_read_b128 v[186:189], v198 offset:16384
	ds_read_b128 v[208:211], v250 offset:16384
	ds_read_b128 v[212:215], v198 offset:18432
	ds_read_b128 v[216:219], v250 offset:18432
	ds_read_b128 v[220:223], v198 offset:20480
	ds_read_b128 v[224:227], v250 offset:20480
	global_load_lds_dwordx4 v166, s[4:5]
	s_add_i32 m0, s96, 0x2000
	s_add_u32 s96, s4, 0x104000
	s_addc_u32 s97, s5, 0
	s_add_i32 s98, s89, s31
	global_load_lds_dwordx4 v170, s[4:5]
	s_mov_b32 m0, s98
	ds_read_b128 v[228:231], v198 offset:22528
	global_load_lds_dwordx4 v166, s[96:97]
	s_add_i32 m0, s98, 0x2000
	ds_read_b128 v[232:235], v250 offset:22528
	global_load_lds_dwordx4 v170, s[96:97]
	s_waitcnt vmcnt(6)
	s_waitcnt lgkmcnt(0)
	s_setprio 2
	s_barrier
; #define PG8_STAGE(bufoff, gbase, voff) do { _Pragma("unroll") for (int _i = 0; _i < 2; ++_i) \
;         __builtin_amdgcn_global_load_lds((const unsigned*)((const char*)(gbase) + (voff)[_i]), (LAS unsigned*)(lds + (bufoff) + ldsw + _i * 8192), 16, 0, 0); } while (0)
; #define PG8_LDA(dst, b, h) do { _Pragma("unroll") for (int m = 0; m < 4; ++m) _Pragma("unroll") for (int k = 0; k < 2; ++k) dst[m][k] = *(const LAS bf16x8*)(lds + PG8_SA(b, h) + aoff + m * 2048 + k * 1024); } while (0)
; #define PG8_LDB(dst, b, h) do { _Pragma("unroll") for (int n = 0; n < 2; ++n) _Pragma("unroll") for (int k = 0; k < 2; ++k) dst[n][k] = *(const LAS bf16x8*)(lds + PG8_SB(b, h) + boff + n * 2048 + k * 1024); } while (0)
; #define PG8_MMA(ai, bj, At, Bt) do { __builtin_amdgcn_s_setprio(3); _Pragma("unroll") for (int m = 0; m < 4; ++m) _Pragma("unroll") for (int n = 0; n < 2; ++n) _Pragma("unroll") for (int k = 0; k < 2; ++k) \
;         acc[ai][bj][m][n] = __builtin_amdgcn_mfma_f32_16x16x32_bf16(Bt[n][k], At[m][k], acc[ai][bj][m][n], 0, 0, 0); __builtin_amdgcn_s_setprio(0); } while (0)
; #define PG8_WAIT_V(n) asm volatile("s_waitcnt vmcnt(" #n ")" ::: "memory")
; #define PG8_WAIT_L(n) asm volatile("s_waitcnt lgkmcnt(" #n ")" ::: "memory")
; #define PG8_BAR __builtin_amdgcn_s_barrier()
; #define PG8_SCHED __builtin_amdgcn_sched_barrier(0)
; template <class Epi, class Sched, bool ALIGN_EPI = false, bool SP2 = false>
; __device__ __forceinline__ void gemm_phase(LAS unsigned char* lds, const Gemm g, const Sched& S, const Epi& E) {
;     ...
;             PG8_WAIT_V(8); PG8_WAIT_L(0); PG8_BAR; PG8_MMA(1, 0, At, B0); PG8_MMA(1, 1, At, B1); PG8_BAR; PG8_SCHED;
;             PG8_LDB(B0, 1, 0); PG8_LDB(B1, 1, 1); PG8_SCHED; PG8_LDA(At, 1, 0); PG8_STAGE(PG8_SA(0, 1), a2 + hsA, voffA);
;             PG8_WAIT_V(8); PG8_WAIT_L(0); PG8_BAR; PG8_MMA(0, 0, At, B0); PG8_MMA(0, 1, At, B1); PG8_BAR; PG8_SCHED;
	v_mfma_f32_16x16x32_bf16 v[64:67], v[84:87], v[186:189], v[64:67]
	v_mfma_f32_16x16x32_bf16 v[64:67], v[96:99], v[208:211], v[64:67]
	v_mfma_f32_16x16x32_bf16 v[60:63], v[140:143], v[186:189], v[60:63]
	v_mfma_f32_16x16x32_bf16 v[60:63], v[144:147], v[208:211], v[60:63]
	v_mfma_f32_16x16x32_bf16 v[48:51], v[84:87], v[212:215], v[48:51]
	v_mfma_f32_16x16x32_bf16 v[48:51], v[96:99], v[216:219], v[48:51]
	v_mfma_f32_16x16x32_bf16 v[44:47], v[140:143], v[212:215], v[44:47]
	v_mfma_f32_16x16x32_bf16 v[44:47], v[144:147], v[216:219], v[44:47]
	v_mfma_f32_16x16x32_bf16 v[32:35], v[84:87], v[220:223], v[32:35]
	v_mfma_f32_16x16x32_bf16 v[32:35], v[96:99], v[224:227], v[32:35]
	v_mfma_f32_16x16x32_bf16 v[28:31], v[140:143], v[220:223], v[28:31]
	v_mfma_f32_16x16x32_bf16 v[28:31], v[144:147], v[224:227], v[28:31]
	v_mfma_f32_16x16x32_bf16 v[16:19], v[84:87], v[228:231], v[16:19]
	v_mfma_f32_16x16x32_bf16 v[16:19], v[96:99], v[232:235], v[16:19]
	v_mfma_f32_16x16x32_bf16 v[12:15], v[140:143], v[228:231], v[12:15]
	v_mfma_f32_16x16x32_bf16 v[12:15], v[144:147], v[232:235], v[12:15]
	s_setprio 0
	s_setprio 2
	v_mfma_f32_16x16x32_bf16 v[56:59], v[152:155], v[186:189], v[56:59]
	v_mfma_f32_16x16x32_bf16 v[56:59], v[156:159], v[208:211], v[56:59]
	v_mfma_f32_16x16x32_bf16 v[52:55], v[160:163], v[186:189], v[52:55]
	v_mfma_f32_16x16x32_bf16 v[52:55], v[182:185], v[208:211], v[52:55]
	v_mfma_f32_16x16x32_bf16 v[40:43], v[152:155], v[212:215], v[40:43]
	v_mfma_f32_16x16x32_bf16 v[40:43], v[156:159], v[216:219], v[40:43]
	v_mfma_f32_16x16x32_bf16 v[36:39], v[160:163], v[212:215], v[36:39]
	v_mfma_f32_16x16x32_bf16 v[36:39], v[182:185], v[216:219], v[36:39]
	v_mfma_f32_16x16x32_bf16 v[24:27], v[152:155], v[220:223], v[24:27]
	v_mfma_f32_16x16x32_bf16 v[24:27], v[156:159], v[224:227], v[24:27]
	v_mfma_f32_16x16x32_bf16 v[20:23], v[160:163], v[220:223], v[20:23]
	v_mfma_f32_16x16x32_bf16 v[20:23], v[182:185], v[224:227], v[20:23]
	v_mfma_f32_16x16x32_bf16 v[8:11], v[152:155], v[228:231], v[8:11]
	v_mfma_f32_16x16x32_bf16 v[8:11], v[156:159], v[232:235], v[8:11]
	v_mfma_f32_16x16x32_bf16 v[2:5], v[160:163], v[228:231], v[4:7]
	s_setprio 3
	s_barrier
	v_mfma_f32_16x16x32_bf16 v[2:5], v[182:185], v[232:235], v[2:5]
	s_setprio 0
	s_add_i32 s96, 0, 0x18000
	v_add_u32_e32 v1, s96, v194
	v_xor_b32_e32 v253, 64, v1
	s_add_i32 s97, 0, 0x1c000
	ds_read_b128 v[84:87], v1
	ds_read_b128 v[96:99], v253
	ds_read_b128 v[140:143], v1 offset:2048
	ds_read_b128 v[144:147], v253 offset:2048
	v_add_u32_e32 v1, s97, v194
	v_xor_b32_e32 v253, 64, v1
	ds_read_b128 v[152:155], v1
	ds_read_b128 v[156:159], v253
	ds_read_b128 v[160:163], v1 offset:2048
	ds_read_b128 v[182:185], v253 offset:2048
	s_mov_b32 m0, s41
	ds_read_b128 v[224:227], v250 offset:36864
	global_load_lds_dwordx4 v164, s[8:9]
	s_mov_b32 m0, s68
	ds_read_b128 v[228:231], v198 offset:38912
	global_load_lds_dwordx4 v168, s[8:9]
	s_add_u32 s8, s8, 0x100000
	s_addc_u32 s9, s9, 0
	s_mov_b32 m0, s69
	ds_read_b128 v[186:189], v198 offset:32768
	ds_read_b128 v[208:211], v250 offset:32768
	ds_read_b128 v[212:215], v198 offset:34816
	ds_read_b128 v[216:219], v250 offset:34816
	ds_read_b128 v[220:223], v198 offset:36864
	global_load_lds_dwordx4 v164, s[8:9]
	s_mov_b32 m0, s70
	ds_read_b128 v[232:235], v250 offset:38912
	global_load_lds_dwordx4 v168, s[8:9]
	s_waitcnt vmcnt(8)
	s_waitcnt lgkmcnt(0)
	s_setprio 2
	s_barrier
; #define PG8_STAGE(bufoff, gbase, voff) do { _Pragma("unroll") for (int _i = 0; _i < 2; ++_i) \
;         __builtin_amdgcn_global_load_lds((const unsigned*)((const char*)(gbase) + (voff)[_i]), (LAS unsigned*)(lds + (bufoff) + ldsw + _i * 8192), 16, 0, 0); } while (0)
; #define PG8_LDA(dst, b, h) do { _Pragma("unroll") for (int m = 0; m < 4; ++m) _Pragma("unroll") for (int k = 0; k < 2; ++k) dst[m][k] = *(const LAS bf16x8*)(lds + PG8_SA(b, h) + aoff + m * 2048 + k * 1024); } while (0)
; #define PG8_MMA(ai, bj, At, Bt) do { __builtin_amdgcn_s_setprio(3); _Pragma("unroll") for (int m = 0; m < 4; ++m) _Pragma("unroll") for (int n = 0; n < 2; ++n) _Pragma("unroll") for (int k = 0; k < 2; ++k) \
;         acc[ai][bj][m][n] = __builtin_amdgcn_mfma_f32_16x16x32_bf16(Bt[n][k], At[m][k], acc[ai][bj][m][n], 0, 0, 0); __builtin_amdgcn_s_setprio(0); } while (0)
; #define PG8_WAIT_V(n) asm volatile("s_waitcnt vmcnt(" #n ")" ::: "memory")
; #define PG8_WAIT_L(n) asm volatile("s_waitcnt lgkmcnt(" #n ")" ::: "memory")
; #define PG8_BAR __builtin_amdgcn_s_barrier()
; #define PG8_SCHED __builtin_amdgcn_sched_barrier(0)
; template <class Epi, class Sched, bool ALIGN_EPI = false, bool SP2 = false>
; __device__ __forceinline__ void gemm_phase(LAS unsigned char* lds, const Gemm g, const Sched& S, const Epi& E) {
;     ...
;             PG8_WAIT_V(8); PG8_WAIT_L(0); PG8_BAR; PG8_MMA(0, 0, At, B0); PG8_MMA(0, 1, At, B1); PG8_BAR; PG8_SCHED;
;             PG8_LDA(At, 1, 1); PG8_STAGE(PG8_SB(1, 0), b3, voffB); PG8_STAGE(PG8_SB(1, 1), b3 + hsB, voffB); PG8_STAGE(PG8_SA(1, 0), a3, voffA);
;             PG8_WAIT_V(8); PG8_WAIT_L(0); PG8_BAR; PG8_MMA(1, 0, At, B0); PG8_MMA(1, 1, At, B1); PG8_BAR; PG8_SCHED;
	v_mfma_f32_16x16x32_bf16 v[136:139], v[84:87], v[186:189], v[136:139]
	v_mfma_f32_16x16x32_bf16 v[136:139], v[96:99], v[208:211], v[136:139]
	v_mfma_f32_16x16x32_bf16 v[132:135], v[140:143], v[186:189], v[132:135]
	v_mfma_f32_16x16x32_bf16 v[132:135], v[144:147], v[208:211], v[132:135]
	v_mfma_f32_16x16x32_bf16 v[120:123], v[84:87], v[212:215], v[120:123]
	v_mfma_f32_16x16x32_bf16 v[120:123], v[96:99], v[216:219], v[120:123]
	v_mfma_f32_16x16x32_bf16 v[116:119], v[140:143], v[212:215], v[116:119]
	v_mfma_f32_16x16x32_bf16 v[116:119], v[144:147], v[216:219], v[116:119]
	v_mfma_f32_16x16x32_bf16 v[104:107], v[84:87], v[220:223], v[104:107]
	v_mfma_f32_16x16x32_bf16 v[104:107], v[96:99], v[224:227], v[104:107]
	v_mfma_f32_16x16x32_bf16 v[100:103], v[140:143], v[220:223], v[100:103]
	v_mfma_f32_16x16x32_bf16 v[100:103], v[144:147], v[224:227], v[100:103]
	v_mfma_f32_16x16x32_bf16 v[80:83], v[84:87], v[228:231], v[80:83]
	v_mfma_f32_16x16x32_bf16 v[80:83], v[96:99], v[232:235], v[80:83]
	v_mfma_f32_16x16x32_bf16 v[76:79], v[140:143], v[228:231], v[76:79]
	v_mfma_f32_16x16x32_bf16 v[76:79], v[144:147], v[232:235], v[76:79]
	s_setprio 0
	s_setprio 2
	v_mfma_f32_16x16x32_bf16 v[128:131], v[152:155], v[186:189], v[128:131]
	v_mfma_f32_16x16x32_bf16 v[128:131], v[156:159], v[208:211], v[128:131]
	v_mfma_f32_16x16x32_bf16 v[124:127], v[160:163], v[186:189], v[124:127]
	v_mfma_f32_16x16x32_bf16 v[124:127], v[182:185], v[208:211], v[124:127]
	v_mfma_f32_16x16x32_bf16 v[112:115], v[152:155], v[212:215], v[112:115]
	v_mfma_f32_16x16x32_bf16 v[112:115], v[156:159], v[216:219], v[112:115]
	v_mfma_f32_16x16x32_bf16 v[108:111], v[160:163], v[212:215], v[108:111]
	v_mfma_f32_16x16x32_bf16 v[108:111], v[182:185], v[216:219], v[108:111]
	v_mfma_f32_16x16x32_bf16 v[92:95], v[152:155], v[220:223], v[92:95]
	v_mfma_f32_16x16x32_bf16 v[92:95], v[156:159], v[224:227], v[92:95]
	v_mfma_f32_16x16x32_bf16 v[88:91], v[160:163], v[220:223], v[88:91]
	v_mfma_f32_16x16x32_bf16 v[88:91], v[182:185], v[224:227], v[88:91]
	v_mfma_f32_16x16x32_bf16 v[72:75], v[152:155], v[228:231], v[72:75]
	v_mfma_f32_16x16x32_bf16 v[72:75], v[156:159], v[232:235], v[72:75]
	v_mfma_f32_16x16x32_bf16 v[68:71], v[160:163], v[228:231], v[68:71]
	s_setprio 3
	s_barrier
	v_mfma_f32_16x16x32_bf16 v[68:71], v[182:185], v[232:235], v[68:71]
	s_setprio 0
	s_add_i32 s8, s96, s31
	s_add_u32 s100, s4, s24
	s_addc_u32 s101, s5, s25
	s_mov_b32 m0, s8
	ds_read_b128 v[186:189], v198 offset:49152
	ds_read_b128 v[208:211], v250 offset:49152
	ds_read_b128 v[212:215], v198 offset:51200
	ds_read_b128 v[216:219], v250 offset:51200
	ds_read_b128 v[220:223], v198 offset:53248
	ds_read_b128 v[224:227], v250 offset:53248
	global_load_lds_dwordx4 v166, s[100:101]
	s_add_i32 m0, s8, 0x2000
	s_add_u32 s4, s4, 0x104080
	s_addc_u32 s5, s5, 0
	s_add_i32 s8, s97, s31
	global_load_lds_dwordx4 v170, s[100:101]
	s_mov_b32 m0, s8
	ds_read_b128 v[228:231], v198 offset:55296
	global_load_lds_dwordx4 v166, s[4:5]
	s_add_i32 m0, s8, 0x2000
	ds_read_b128 v[232:235], v250 offset:55296
	global_load_lds_dwordx4 v170, s[4:5]
	s_waitcnt vmcnt(6)
	s_waitcnt lgkmcnt(0)
	s_setprio 2
	s_barrier
	v_mfma_f32_16x16x32_bf16 v[64:67], v[84:87], v[186:189], v[64:67]
	v_mfma_f32_16x16x32_bf16 v[64:67], v[96:99], v[208:211], v[64:67]
	v_mfma_f32_16x16x32_bf16 v[60:63], v[140:143], v[186:189], v[60:63]
	v_mfma_f32_16x16x32_bf16 v[60:63], v[144:147], v[208:211], v[60:63]
	v_mfma_f32_16x16x32_bf16 v[48:51], v[84:87], v[212:215], v[48:51]
	v_mfma_f32_16x16x32_bf16 v[48:51], v[96:99], v[216:219], v[48:51]
	v_mfma_f32_16x16x32_bf16 v[44:47], v[140:143], v[212:215], v[44:47]
	v_mfma_f32_16x16x32_bf16 v[44:47], v[144:147], v[216:219], v[44:47]
	v_mfma_f32_16x16x32_bf16 v[32:35], v[84:87], v[220:223], v[32:35]
	v_mfma_f32_16x16x32_bf16 v[32:35], v[96:99], v[224:227], v[32:35]
	v_mfma_f32_16x16x32_bf16 v[28:31], v[140:143], v[220:223], v[28:31]
	v_mfma_f32_16x16x32_bf16 v[28:31], v[144:147], v[224:227], v[28:31]
	v_mfma_f32_16x16x32_bf16 v[16:19], v[84:87], v[228:231], v[16:19]
	v_mfma_f32_16x16x32_bf16 v[16:19], v[96:99], v[232:235], v[16:19]
	v_mfma_f32_16x16x32_bf16 v[12:15], v[140:143], v[228:231], v[12:15]
	v_mfma_f32_16x16x32_bf16 v[12:15], v[144:147], v[232:235], v[12:15]
	s_setprio 0
	s_setprio 2
	v_mfma_f32_16x16x32_bf16 v[56:59], v[152:155], v[186:189], v[56:59]
	v_mfma_f32_16x16x32_bf16 v[56:59], v[156:159], v[208:211], v[56:59]
	v_mfma_f32_16x16x32_bf16 v[52:55], v[160:163], v[186:189], v[52:55]
	v_mfma_f32_16x16x32_bf16 v[52:55], v[182:185], v[208:211], v[52:55]
	v_mfma_f32_16x16x32_bf16 v[40:43], v[152:155], v[212:215], v[40:43]
	v_mfma_f32_16x16x32_bf16 v[40:43], v[156:159], v[216:219], v[40:43]
	v_mfma_f32_16x16x32_bf16 v[36:39], v[160:163], v[212:215], v[36:39]
	v_mfma_f32_16x16x32_bf16 v[36:39], v[182:185], v[216:219], v[36:39]
	v_mfma_f32_16x16x32_bf16 v[24:27], v[152:155], v[220:223], v[24:27]
	v_mfma_f32_16x16x32_bf16 v[24:27], v[156:159], v[224:227], v[24:27]
	v_mfma_f32_16x16x32_bf16 v[20:23], v[160:163], v[220:223], v[20:23]
	v_mfma_f32_16x16x32_bf16 v[20:23], v[182:185], v[224:227], v[20:23]
	v_mfma_f32_16x16x32_bf16 v[6:9], v[152:155], v[228:231], v[8:11]
	v_mfma_f32_16x16x32_bf16 v[8:11], v[156:159], v[232:235], v[6:9]
	v_mfma_f32_16x16x32_bf16 v[2:5], v[160:163], v[228:231], v[2:5]
	s_setprio 3
	s_barrier
	v_mfma_f32_16x16x32_bf16 v[4:7], v[182:185], v[232:235], v[2:5]
	s_setprio 0
	s_add_i32 s95, s95, 2
	s_add_u32 s66, s66, 0x100
	s_addc_u32 s67, s67, 0
	s_cmp_gt_u32 s95, 61
	s_cbranch_scc1 .LBB0_237

; #define PG8_STAGE(bufoff, gbase, voff) do { _Pragma("unroll") for (int _i = 0; _i < 2; ++_i) \
;         __builtin_amdgcn_global_load_lds((const unsigned*)((const char*)(gbase) + (voff)[_i]), (LAS unsigned*)(lds + (bufoff) + ldsw + _i * 8192), 16, 0, 0); } while (0)
; #define PG8_LDA(dst, b, h) do { _Pragma("unroll") for (int m = 0; m < 4; ++m) _Pragma("unroll") for (int k = 0; k < 2; ++k) dst[m][k] = *(const LAS bf16x8*)(lds + PG8_SA(b, h) + aoff + m * 2048 + k * 1024); } while (0)
; #define PG8_LDB(dst, b, h) do { _Pragma("unroll") for (int n = 0; n < 2; ++n) _Pragma("unroll") for (int k = 0; k < 2; ++k) dst[n][k] = *(const LAS bf16x8*)(lds + PG8_SB(b, h) + boff + n * 2048 + k * 1024); } while (0)
; #define PG8_MMA(ai, bj, At, Bt) do { __builtin_amdgcn_s_setprio(3); _Pragma("unroll") for (int m = 0; m < 4; ++m) _Pragma("unroll") for (int n = 0; n < 2; ++n) _Pragma("unroll") for (int k = 0; k < 2; ++k) \
;         acc[ai][bj][m][n] = __builtin_amdgcn_mfma_f32_16x16x32_bf16(Bt[n][k], At[m][k], acc[ai][bj][m][n], 0, 0, 0); __builtin_amdgcn_s_setprio(0); } while (0)
; #define PG8_WAIT_V(n) asm volatile("s_waitcnt vmcnt(" #n ")" ::: "memory")
; #define PG8_WAIT_L(n) asm volatile("s_waitcnt lgkmcnt(" #n ")" ::: "memory")
; #define PG8_BAR __builtin_amdgcn_s_barrier()
; #define PG8_SCHED __builtin_amdgcn_sched_barrier(0)
; template <class Epi, class Sched, bool ALIGN_EPI = false, bool SP2 = false>
; __device__ __forceinline__ void gemm_phase(LAS unsigned char* lds, const Gemm g, const Sched& S, const Epi& E) {
;     ...
;             PG8_LDB(B0, 0, 0); PG8_LDB(B1, 0, 1); PG8_SCHED; PG8_LDA(At, 0, 0); PG8_STAGE(PG8_SA(1, 1), a1 + hsA, voffA);
;             PG8_WAIT_V(8); PG8_WAIT_L(0); PG8_BAR; PG8_MMA(0, 0, At, B0); PG8_MMA(0, 1, At, B1); PG8_BAR; PG8_SCHED;
;             PG8_LDA(At, 0, 1); PG8_STAGE(PG8_SB(0, 0), b2, voffB); PG8_STAGE(PG8_SB(0, 1), b2 + hsB, voffB); PG8_STAGE(PG8_SA(0, 0), a2, voffA);
;             PG8_WAIT_V(8); PG8_WAIT_L(0); PG8_BAR; PG8_MMA(1, 0, At, B0); PG8_MMA(1, 1, At, B1); PG8_BAR; PG8_SCHED;
.LBB0_309:
	ds_read_b128 v[112:115], v175
	ds_read_b128 v[132:135], v251
	ds_read_b128 v[136:139], v175 offset:2048
	ds_read_b128 v[140:143], v251 offset:2048
	ds_read_b128 v[144:147], v176
	ds_read_b128 v[148:151], v252
	ds_read_b128 v[184:187], v176 offset:2048
	ds_read_b128 v[188:191], v252 offset:2048
	s_add_u32 s24, s4, 0xffefc080
	s_addc_u32 s25, s5, -1
	s_cmp_eq_u32 s73, 60
	s_cselect_b32 s27, s11, s25
	s_cselect_b32 s26, s10, s24
	s_cselect_b32 s25, s21, s72
	s_cselect_b32 s24, s20, s71
	s_sub_u32 s100, s4, 0x104000
	s_subb_u32 s101, s5, 0
	s_mov_b32 m0, s42
	ds_read_b128 v[218:221], v250 offset:4096
	global_load_lds_dwordx4 v152, s[100:101]
	s_mov_b32 m0, s43
	ds_read_b128 v[222:225], v177 offset:6144
	global_load_lds_dwordx4 v156, s[100:101]
	s_add_i32 m0, s36, 0xc000
	ds_read_b128 v[192:195], v177
	ds_read_b128 v[196:199], v250
	ds_read_b128 v[206:209], v177 offset:2048
	ds_read_b128 v[210:213], v250 offset:2048
	ds_read_b128 v[214:217], v177 offset:4096
	global_load_lds_dwordx4 v164, s[4:5]
	s_add_i32 m0, s36, 0xe000
	ds_read_b128 v[226:229], v250 offset:6144
	global_load_lds_dwordx4 v166, s[4:5]
	s_waitcnt vmcnt(8)
	s_waitcnt lgkmcnt(0)
	s_setprio 2
	s_barrier
	v_mfma_f32_16x16x32_bf16 v[128:131], v[112:115], v[192:195], v[128:131]
	v_mfma_f32_16x16x32_bf16 v[128:131], v[132:135], v[196:199], v[128:131]
	v_mfma_f32_16x16x32_bf16 v[124:127], v[136:139], v[192:195], v[124:127]
	v_mfma_f32_16x16x32_bf16 v[124:127], v[140:143], v[196:199], v[124:127]
	v_mfma_f32_16x16x32_bf16 v[108:111], v[112:115], v[206:209], v[108:111]
	v_mfma_f32_16x16x32_bf16 v[108:111], v[132:135], v[210:213], v[108:111]
	v_mfma_f32_16x16x32_bf16 v[104:107], v[136:139], v[206:209], v[104:107]
	v_mfma_f32_16x16x32_bf16 v[104:107], v[140:143], v[210:213], v[104:107]
	v_mfma_f32_16x16x32_bf16 v[92:95], v[112:115], v[214:217], v[92:95]
	v_mfma_f32_16x16x32_bf16 v[92:95], v[132:135], v[218:221], v[92:95]
	v_mfma_f32_16x16x32_bf16 v[88:91], v[136:139], v[214:217], v[88:91]
	v_mfma_f32_16x16x32_bf16 v[88:91], v[140:143], v[218:221], v[88:91]
	v_mfma_f32_16x16x32_bf16 v[76:79], v[112:115], v[222:225], v[76:79]
	v_mfma_f32_16x16x32_bf16 v[76:79], v[132:135], v[226:229], v[76:79]
	v_mfma_f32_16x16x32_bf16 v[72:75], v[136:139], v[222:225], v[72:75]
	v_mfma_f32_16x16x32_bf16 v[72:75], v[140:143], v[226:229], v[72:75]
	s_setprio 0
	s_setprio 2
	v_mfma_f32_16x16x32_bf16 v[120:123], v[144:147], v[192:195], v[120:123]
	v_mfma_f32_16x16x32_bf16 v[120:123], v[148:151], v[196:199], v[120:123]
	v_mfma_f32_16x16x32_bf16 v[116:119], v[184:187], v[192:195], v[116:119]
	v_mfma_f32_16x16x32_bf16 v[116:119], v[188:191], v[196:199], v[116:119]
	v_mfma_f32_16x16x32_bf16 v[100:103], v[144:147], v[206:209], v[100:103]
	v_mfma_f32_16x16x32_bf16 v[100:103], v[148:151], v[210:213], v[100:103]
	v_mfma_f32_16x16x32_bf16 v[96:99], v[184:187], v[206:209], v[96:99]
	v_mfma_f32_16x16x32_bf16 v[96:99], v[188:191], v[210:213], v[96:99]
	v_mfma_f32_16x16x32_bf16 v[84:87], v[144:147], v[214:217], v[84:87]
	v_mfma_f32_16x16x32_bf16 v[84:87], v[148:151], v[218:221], v[84:87]
	v_mfma_f32_16x16x32_bf16 v[80:83], v[184:187], v[214:217], v[80:83]
	v_mfma_f32_16x16x32_bf16 v[80:83], v[188:191], v[218:221], v[80:83]
	v_mfma_f32_16x16x32_bf16 v[68:71], v[144:147], v[222:225], v[68:71]
	v_mfma_f32_16x16x32_bf16 v[68:71], v[148:151], v[226:229], v[68:71]
	v_mfma_f32_16x16x32_bf16 v[64:67], v[184:187], v[222:225], v[64:67]
	s_setprio 3
	s_barrier
	v_mfma_f32_16x16x32_bf16 v[64:67], v[188:191], v[226:229], v[64:67]
	s_setprio 0
	s_add_i32 s74, s45, s31
	s_mov_b32 m0, s74
	ds_read_b128 v[192:195], v177 offset:16384
	ds_read_b128 v[196:199], v250 offset:16384
	ds_read_b128 v[206:209], v177 offset:18432
	ds_read_b128 v[210:213], v250 offset:18432
	ds_read_b128 v[214:217], v177 offset:20480
	ds_read_b128 v[218:221], v250 offset:20480
	global_load_lds_dwordx4 v154, s[24:25]
	s_add_i32 m0, s74, 0x2000
	s_add_u32 s74, s24, 0x41000
	s_addc_u32 s75, s25, 0
	s_add_i32 s78, s46, s31
	global_load_lds_dwordx4 v158, s[24:25]
	s_mov_b32 m0, s78
	ds_read_b128 v[222:225], v177 offset:22528
	global_load_lds_dwordx4 v154, s[74:75]
	s_add_i32 m0, s78, 0x2000
	ds_read_b128 v[226:229], v250 offset:22528
	global_load_lds_dwordx4 v158, s[74:75]
	s_waitcnt vmcnt(6)
	s_waitcnt lgkmcnt(0)
	s_setprio 2
	s_barrier
	v_mfma_f32_16x16x32_bf16 v[60:63], v[112:115], v[192:195], v[60:63]
	v_mfma_f32_16x16x32_bf16 v[60:63], v[132:135], v[196:199], v[60:63]
	v_mfma_f32_16x16x32_bf16 v[56:59], v[136:139], v[192:195], v[56:59]
	v_mfma_f32_16x16x32_bf16 v[56:59], v[140:143], v[196:199], v[56:59]
	v_mfma_f32_16x16x32_bf16 v[44:47], v[112:115], v[206:209], v[44:47]
	v_mfma_f32_16x16x32_bf16 v[44:47], v[132:135], v[210:213], v[44:47]
	v_mfma_f32_16x16x32_bf16 v[40:43], v[136:139], v[206:209], v[40:43]
	v_mfma_f32_16x16x32_bf16 v[40:43], v[140:143], v[210:213], v[40:43]
	v_mfma_f32_16x16x32_bf16 v[28:31], v[112:115], v[214:217], v[28:31]
	v_mfma_f32_16x16x32_bf16 v[28:31], v[132:135], v[218:221], v[28:31]
	v_mfma_f32_16x16x32_bf16 v[24:27], v[136:139], v[214:217], v[24:27]
	v_mfma_f32_16x16x32_bf16 v[24:27], v[140:143], v[218:221], v[24:27]
	v_mfma_f32_16x16x32_bf16 v[12:15], v[112:115], v[222:225], v[12:15]
	v_mfma_f32_16x16x32_bf16 v[12:15], v[132:135], v[226:229], v[12:15]
	v_mfma_f32_16x16x32_bf16 v[8:11], v[136:139], v[222:225], v[8:11]
	v_mfma_f32_16x16x32_bf16 v[8:11], v[140:143], v[226:229], v[8:11]
	s_setprio 0
	s_setprio 2
	v_mfma_f32_16x16x32_bf16 v[52:55], v[144:147], v[192:195], v[52:55]
	v_mfma_f32_16x16x32_bf16 v[52:55], v[148:151], v[196:199], v[52:55]
	v_mfma_f32_16x16x32_bf16 v[48:51], v[184:187], v[192:195], v[48:51]
	v_mfma_f32_16x16x32_bf16 v[48:51], v[188:191], v[196:199], v[48:51]
	v_mfma_f32_16x16x32_bf16 v[36:39], v[144:147], v[206:209], v[36:39]
	v_mfma_f32_16x16x32_bf16 v[36:39], v[148:151], v[210:213], v[36:39]
	v_mfma_f32_16x16x32_bf16 v[32:35], v[184:187], v[206:209], v[32:35]
	v_mfma_f32_16x16x32_bf16 v[32:35], v[188:191], v[210:213], v[32:35]
	v_mfma_f32_16x16x32_bf16 v[20:23], v[144:147], v[214:217], v[20:23]
	v_mfma_f32_16x16x32_bf16 v[20:23], v[148:151], v[218:221], v[20:23]
	v_mfma_f32_16x16x32_bf16 v[16:19], v[184:187], v[214:217], v[16:19]
	v_mfma_f32_16x16x32_bf16 v[16:19], v[188:191], v[218:221], v[16:19]
	v_mfma_f32_16x16x32_bf16 v[4:7], v[144:147], v[222:225], v[4:7]
	v_mfma_f32_16x16x32_bf16 v[4:7], v[148:151], v[226:229], v[4:7]
	v_mfma_f32_16x16x32_bf16 v[0:3], v[184:187], v[222:225], v[0:3]
	s_setprio 3
	s_barrier
; #define PG8_STAGE(bufoff, gbase, voff) do { _Pragma("unroll") for (int _i = 0; _i < 2; ++_i) \
;         __builtin_amdgcn_global_load_lds((const unsigned*)((const char*)(gbase) + (voff)[_i]), (LAS unsigned*)(lds + (bufoff) + ldsw + _i * 8192), 16, 0, 0); } while (0)
; #define PG8_LDA(dst, b, h) do { _Pragma("unroll") for (int m = 0; m < 4; ++m) _Pragma("unroll") for (int k = 0; k < 2; ++k) dst[m][k] = *(const LAS bf16x8*)(lds + PG8_SA(b, h) + aoff + m * 2048 + k * 1024); } while (0)
; #define PG8_LDB(dst, b, h) do { _Pragma("unroll") for (int n = 0; n < 2; ++n) _Pragma("unroll") for (int k = 0; k < 2; ++k) dst[n][k] = *(const LAS bf16x8*)(lds + PG8_SB(b, h) + boff + n * 2048 + k * 1024); } while (0)
; #define PG8_MMA(ai, bj, At, Bt) do { __builtin_amdgcn_s_setprio(3); _Pragma("unroll") for (int m = 0; m < 4; ++m) _Pragma("unroll") for (int n = 0; n < 2; ++n) _Pragma("unroll") for (int k = 0; k < 2; ++k) \
;         acc[ai][bj][m][n] = __builtin_amdgcn_mfma_f32_16x16x32_bf16(Bt[n][k], At[m][k], acc[ai][bj][m][n], 0, 0, 0); __builtin_amdgcn_s_setprio(0); } while (0)
; #define PG8_WAIT_V(n) asm volatile("s_waitcnt vmcnt(" #n ")" ::: "memory")
; #define PG8_WAIT_L(n) asm volatile("s_waitcnt lgkmcnt(" #n ")" ::: "memory")
; #define PG8_BAR __builtin_amdgcn_s_barrier()
; #define PG8_SCHED __builtin_amdgcn_sched_barrier(0)
; template <class Epi, class Sched, bool ALIGN_EPI = false, bool SP2 = false>
; __device__ __forceinline__ void gemm_phase(LAS unsigned char* lds, const Gemm g, const Sched& S, const Epi& E) {
;     ...
;             PG8_LDB(B0, 1, 0); PG8_LDB(B1, 1, 1); PG8_SCHED; PG8_LDA(At, 1, 0); PG8_STAGE(PG8_SA(0, 1), a2 + hsA, voffA);
;             PG8_WAIT_V(8); PG8_WAIT_L(0); PG8_BAR; PG8_MMA(0, 0, At, B0); PG8_MMA(0, 1, At, B1); PG8_BAR; PG8_SCHED;
;             PG8_LDA(At, 1, 1); PG8_STAGE(PG8_SB(1, 0), b3, voffB); PG8_STAGE(PG8_SB(1, 1), b3 + hsB, voffB); PG8_STAGE(PG8_SA(1, 0), a3, voffA);
;             PG8_WAIT_V(8); PG8_WAIT_L(0); PG8_BAR; PG8_MMA(1, 0, At, B0); PG8_MMA(1, 1, At, B1); PG8_BAR; PG8_SCHED;
	v_mfma_f32_16x16x32_bf16 v[0:3], v[188:191], v[226:229], v[0:3]
	s_setprio 0
	s_add_i32 s74, 0, 0x18000
	s_add_i32 s75, 0, 0x1c000
	ds_read_b128 v[112:115], v246
	ds_read_b128 v[132:135], v247
	ds_read_b128 v[136:139], v246 offset:2048
	ds_read_b128 v[140:143], v247 offset:2048
	ds_read_b128 v[144:147], v248
	ds_read_b128 v[148:151], v249
	ds_read_b128 v[184:187], v248 offset:2048
	ds_read_b128 v[188:191], v249 offset:2048
	s_mov_b32 m0, s36
	ds_read_b128 v[218:221], v250 offset:36864
	global_load_lds_dwordx4 v152, s[26:27]
	s_mov_b32 m0, s37
	ds_read_b128 v[222:225], v177 offset:38912
	global_load_lds_dwordx4 v156, s[26:27]
	s_add_u32 s26, s26, 0x104000
	s_addc_u32 s27, s27, 0
	s_mov_b32 m0, s38
	ds_read_b128 v[192:195], v177 offset:32768
	ds_read_b128 v[196:199], v250 offset:32768
	ds_read_b128 v[206:209], v177 offset:34816
	ds_read_b128 v[210:213], v250 offset:34816
	ds_read_b128 v[214:217], v177 offset:36864
	global_load_lds_dwordx4 v152, s[26:27]
	s_mov_b32 m0, s39
	ds_read_b128 v[226:229], v250 offset:38912
	global_load_lds_dwordx4 v156, s[26:27]
	s_waitcnt vmcnt(8)
	s_waitcnt lgkmcnt(0)
	s_setprio 2
	s_barrier
	v_mfma_f32_16x16x32_bf16 v[128:131], v[112:115], v[192:195], v[128:131]
	v_mfma_f32_16x16x32_bf16 v[128:131], v[132:135], v[196:199], v[128:131]
	v_mfma_f32_16x16x32_bf16 v[124:127], v[136:139], v[192:195], v[124:127]
	v_mfma_f32_16x16x32_bf16 v[124:127], v[140:143], v[196:199], v[124:127]
	v_mfma_f32_16x16x32_bf16 v[108:111], v[112:115], v[206:209], v[108:111]
	v_mfma_f32_16x16x32_bf16 v[108:111], v[132:135], v[210:213], v[108:111]
	v_mfma_f32_16x16x32_bf16 v[104:107], v[136:139], v[206:209], v[104:107]
	v_mfma_f32_16x16x32_bf16 v[104:107], v[140:143], v[210:213], v[104:107]
	v_mfma_f32_16x16x32_bf16 v[92:95], v[112:115], v[214:217], v[92:95]
	v_mfma_f32_16x16x32_bf16 v[92:95], v[132:135], v[218:221], v[92:95]
	v_mfma_f32_16x16x32_bf16 v[88:91], v[136:139], v[214:217], v[88:91]
	v_mfma_f32_16x16x32_bf16 v[88:91], v[140:143], v[218:221], v[88:91]
	v_mfma_f32_16x16x32_bf16 v[76:79], v[112:115], v[222:225], v[76:79]
	v_mfma_f32_16x16x32_bf16 v[76:79], v[132:135], v[226:229], v[76:79]
	v_mfma_f32_16x16x32_bf16 v[72:75], v[136:139], v[222:225], v[72:75]
	v_mfma_f32_16x16x32_bf16 v[72:75], v[140:143], v[226:229], v[72:75]
	s_setprio 0
	s_setprio 2
	v_mfma_f32_16x16x32_bf16 v[120:123], v[144:147], v[192:195], v[120:123]
	v_mfma_f32_16x16x32_bf16 v[120:123], v[148:151], v[196:199], v[120:123]
	v_mfma_f32_16x16x32_bf16 v[116:119], v[184:187], v[192:195], v[116:119]
	v_mfma_f32_16x16x32_bf16 v[116:119], v[188:191], v[196:199], v[116:119]
	v_mfma_f32_16x16x32_bf16 v[100:103], v[144:147], v[206:209], v[100:103]
	v_mfma_f32_16x16x32_bf16 v[100:103], v[148:151], v[210:213], v[100:103]
	v_mfma_f32_16x16x32_bf16 v[96:99], v[184:187], v[206:209], v[96:99]
	v_mfma_f32_16x16x32_bf16 v[96:99], v[188:191], v[210:213], v[96:99]
	v_mfma_f32_16x16x32_bf16 v[84:87], v[144:147], v[214:217], v[84:87]
	v_mfma_f32_16x16x32_bf16 v[84:87], v[148:151], v[218:221], v[84:87]
	v_mfma_f32_16x16x32_bf16 v[80:83], v[184:187], v[214:217], v[80:83]
	v_mfma_f32_16x16x32_bf16 v[80:83], v[188:191], v[218:221], v[80:83]
	v_mfma_f32_16x16x32_bf16 v[68:71], v[144:147], v[222:225], v[68:71]
	v_mfma_f32_16x16x32_bf16 v[68:71], v[148:151], v[226:229], v[68:71]
	v_mfma_f32_16x16x32_bf16 v[64:67], v[184:187], v[222:225], v[64:67]
	s_setprio 3
	s_barrier
	v_mfma_f32_16x16x32_bf16 v[64:67], v[188:191], v[226:229], v[64:67]
	s_setprio 0
	s_add_i32 s26, s74, s31
	s_add_u32 s100, s24, s14
	s_addc_u32 s101, s25, s15
	s_mov_b32 m0, s26
	ds_read_b128 v[192:195], v177 offset:49152
	ds_read_b128 v[196:199], v250 offset:49152
	ds_read_b128 v[206:209], v177 offset:51200
	ds_read_b128 v[210:213], v250 offset:51200
	ds_read_b128 v[214:217], v177 offset:53248
	ds_read_b128 v[218:221], v250 offset:53248
	global_load_lds_dwordx4 v154, s[100:101]
	s_add_i32 m0, s26, 0x2000
	s_add_u32 s24, s24, 0x41080
	s_addc_u32 s25, s25, 0
	s_add_i32 s26, s75, s31
	global_load_lds_dwordx4 v158, s[100:101]
	s_mov_b32 m0, s26
	ds_read_b128 v[222:225], v177 offset:55296
	global_load_lds_dwordx4 v154, s[24:25]
	s_add_i32 m0, s26, 0x2000
	ds_read_b128 v[226:229], v250 offset:55296
	global_load_lds_dwordx4 v158, s[24:25]
	s_waitcnt vmcnt(6)
	s_waitcnt lgkmcnt(0)
	s_setprio 2
	s_barrier
	v_mfma_f32_16x16x32_bf16 v[60:63], v[112:115], v[192:195], v[60:63]
	v_mfma_f32_16x16x32_bf16 v[60:63], v[132:135], v[196:199], v[60:63]
	v_mfma_f32_16x16x32_bf16 v[56:59], v[136:139], v[192:195], v[56:59]
	v_mfma_f32_16x16x32_bf16 v[56:59], v[140:143], v[196:199], v[56:59]
	v_mfma_f32_16x16x32_bf16 v[44:47], v[112:115], v[206:209], v[44:47]
	v_mfma_f32_16x16x32_bf16 v[44:47], v[132:135], v[210:213], v[44:47]
	v_mfma_f32_16x16x32_bf16 v[40:43], v[136:139], v[206:209], v[40:43]
	v_mfma_f32_16x16x32_bf16 v[40:43], v[140:143], v[210:213], v[40:43]
	v_mfma_f32_16x16x32_bf16 v[28:31], v[112:115], v[214:217], v[28:31]
	v_mfma_f32_16x16x32_bf16 v[28:31], v[132:135], v[218:221], v[28:31]
	v_mfma_f32_16x16x32_bf16 v[24:27], v[136:139], v[214:217], v[24:27]
	v_mfma_f32_16x16x32_bf16 v[24:27], v[140:143], v[218:221], v[24:27]
	v_mfma_f32_16x16x32_bf16 v[12:15], v[112:115], v[222:225], v[12:15]
	v_mfma_f32_16x16x32_bf16 v[12:15], v[132:135], v[226:229], v[12:15]
	v_mfma_f32_16x16x32_bf16 v[8:11], v[136:139], v[222:225], v[8:11]
	v_mfma_f32_16x16x32_bf16 v[8:11], v[140:143], v[226:229], v[8:11]
	s_setprio 0
	s_setprio 2
	v_mfma_f32_16x16x32_bf16 v[52:55], v[144:147], v[192:195], v[52:55]
	v_mfma_f32_16x16x32_bf16 v[52:55], v[148:151], v[196:199], v[52:55]
	v_mfma_f32_16x16x32_bf16 v[48:51], v[184:187], v[192:195], v[48:51]
	v_mfma_f32_16x16x32_bf16 v[48:51], v[188:191], v[196:199], v[48:51]
	v_mfma_f32_16x16x32_bf16 v[36:39], v[144:147], v[206:209], v[36:39]
	v_mfma_f32_16x16x32_bf16 v[36:39], v[148:151], v[210:213], v[36:39]
	v_mfma_f32_16x16x32_bf16 v[32:35], v[184:187], v[206:209], v[32:35]
	v_mfma_f32_16x16x32_bf16 v[32:35], v[188:191], v[210:213], v[32:35]
	v_mfma_f32_16x16x32_bf16 v[20:23], v[144:147], v[214:217], v[20:23]
	v_mfma_f32_16x16x32_bf16 v[20:23], v[148:151], v[218:221], v[20:23]
	v_mfma_f32_16x16x32_bf16 v[16:19], v[184:187], v[214:217], v[16:19]
	v_mfma_f32_16x16x32_bf16 v[16:19], v[188:191], v[218:221], v[16:19]
	v_mfma_f32_16x16x32_bf16 v[4:7], v[144:147], v[222:225], v[4:7]
	v_mfma_f32_16x16x32_bf16 v[4:7], v[148:151], v[226:229], v[4:7]
	v_mfma_f32_16x16x32_bf16 v[0:3], v[184:187], v[222:225], v[0:3]
	s_setprio 3
	s_barrier
	v_mfma_f32_16x16x32_bf16 v[0:3], v[188:191], v[226:229], v[0:3]
	s_setprio 0
	s_add_i32 s73, s73, 2
	s_add_u32 s4, s4, 0x100
	s_addc_u32 s5, s5, 0
	s_add_u32 s71, s71, 0x100
	s_addc_u32 s72, s72, 0
	s_cmp_gt_u32 s73, 61
	s_cbranch_scc0 .LBB0_309
	s_and_b64 vcc, exec, s[16:17]
	s_cbranch_vccz .LBB0_312
	s_barrier

; #define PG8_STAGE(bufoff, gbase, voff) do { _Pragma("unroll") for (int _i = 0; _i < 2; ++_i) \
;         __builtin_amdgcn_global_load_lds((const unsigned*)((const char*)(gbase) + (voff)[_i]), (LAS unsigned*)(lds + (bufoff) + ldsw + _i * 8192), 16, 0, 0); } while (0)
; #define PG8_LDA(dst, b, h) do { _Pragma("unroll") for (int m = 0; m < 4; ++m) _Pragma("unroll") for (int k = 0; k < 2; ++k) dst[m][k] = *(const LAS bf16x8*)(lds + PG8_SA(b, h) + aoff + m * 2048 + k * 1024); } while (0)
; #define PG8_LDB(dst, b, h) do { _Pragma("unroll") for (int n = 0; n < 2; ++n) _Pragma("unroll") for (int k = 0; k < 2; ++k) dst[n][k] = *(const LAS bf16x8*)(lds + PG8_SB(b, h) + boff + n * 2048 + k * 1024); } while (0)
; #define PG8_MMA(ai, bj, At, Bt) do { __builtin_amdgcn_s_setprio(3); _Pragma("unroll") for (int m = 0; m < 4; ++m) _Pragma("unroll") for (int n = 0; n < 2; ++n) _Pragma("unroll") for (int k = 0; k < 2; ++k) \
;         acc[ai][bj][m][n] = __builtin_amdgcn_mfma_f32_16x16x32_bf16(Bt[n][k], At[m][k], acc[ai][bj][m][n], 0, 0, 0); __builtin_amdgcn_s_setprio(0); } while (0)
; #define PG8_WAIT_V(n) asm volatile("s_waitcnt vmcnt(" #n ")" ::: "memory")
; #define PG8_WAIT_L(n) asm volatile("s_waitcnt lgkmcnt(" #n ")" ::: "memory")
; #define PG8_BAR __builtin_amdgcn_s_barrier()
; #define PG8_SCHED __builtin_amdgcn_sched_barrier(0)
; template <class Epi, class Sched, bool ALIGN_EPI = false, bool SP2 = false>
; __device__ __forceinline__ void gemm_phase(LAS unsigned char* lds, const Gemm g, const Sched& S, const Epi& E) {
;     ...
;             PG8_LDB(B0, 0, 0); PG8_LDB(B1, 0, 1); PG8_SCHED; PG8_LDA(At, 0, 0); PG8_STAGE(PG8_SA(1, 1), a1 + hsA, voffA);
;             PG8_WAIT_V(8); PG8_WAIT_L(0); PG8_BAR; PG8_MMA(0, 0, At, B0); PG8_MMA(0, 1, At, B1); PG8_BAR; PG8_SCHED;
;             PG8_LDA(At, 0, 1); PG8_STAGE(PG8_SB(0, 0), b2, voffB); PG8_STAGE(PG8_SB(0, 1), b2 + hsB, voffB); PG8_STAGE(PG8_SA(0, 0), a2, voffA);
;             PG8_WAIT_V(8); PG8_WAIT_L(0); PG8_BAR; PG8_MMA(1, 0, At, B0); PG8_MMA(1, 1, At, B1); PG8_BAR; PG8_SCHED;
.LBB0_350:
	ds_read_b128 v[140:143], v149
	ds_read_b128 v[156:159], v251
	ds_read_b128 v[160:163], v149 offset:2048
	ds_read_b128 v[164:167], v251 offset:2048
	ds_read_b128 v[168:171], v150
	ds_read_b128 v[172:175], v252
	ds_read_b128 v[176:179], v150 offset:2048
	ds_read_b128 v[180:183], v252 offset:2048
	s_add_u32 s16, s14, 0xffbfc080
	s_addc_u32 s17, s15, -1
	s_cmpk_eq_i32 s50, 0xfc
	s_cselect_b32 s21, s5, s17
	s_cselect_b32 s20, s4, s16
	s_cselect_b32 s17, s13, s49
	s_cselect_b32 s16, s12, s48
	s_sub_u32 s100, s14, 0x404000
	s_subb_u32 s101, s15, 0
	s_mov_b32 m0, s33
	ds_read_b128 v[204:207], v250 offset:4096
	global_load_lds_dwordx4 v128, s[100:101]
	s_mov_b32 m0, s38
	ds_read_b128 v[208:211], v151 offset:6144
	global_load_lds_dwordx4 v130, s[100:101]
	s_add_i32 m0, s26, 0xc000
	ds_read_b128 v[184:187], v151
	ds_read_b128 v[188:191], v250
	ds_read_b128 v[192:195], v151 offset:2048
	ds_read_b128 v[196:199], v250 offset:2048
	ds_read_b128 v[200:203], v151 offset:4096
	global_load_lds_dwordx4 v132, s[14:15]
	s_add_i32 m0, s26, 0xe000
	ds_read_b128 v[212:215], v250 offset:6144
	global_load_lds_dwordx4 v134, s[14:15]
	s_waitcnt vmcnt(8)
	s_waitcnt lgkmcnt(0)
	s_setprio 2
	s_barrier
	v_mfma_f32_16x16x32_bf16 v[124:127], v[140:143], v[184:187], v[124:127]
	v_mfma_f32_16x16x32_bf16 v[124:127], v[156:159], v[188:191], v[124:127]
	v_mfma_f32_16x16x32_bf16 v[120:123], v[160:163], v[184:187], v[120:123]
	v_mfma_f32_16x16x32_bf16 v[120:123], v[164:167], v[188:191], v[120:123]
	v_mfma_f32_16x16x32_bf16 v[108:111], v[140:143], v[192:195], v[108:111]
	v_mfma_f32_16x16x32_bf16 v[108:111], v[156:159], v[196:199], v[108:111]
	v_mfma_f32_16x16x32_bf16 v[104:107], v[160:163], v[192:195], v[104:107]
	v_mfma_f32_16x16x32_bf16 v[104:107], v[164:167], v[196:199], v[104:107]
	v_mfma_f32_16x16x32_bf16 v[92:95], v[140:143], v[200:203], v[92:95]
	v_mfma_f32_16x16x32_bf16 v[92:95], v[156:159], v[204:207], v[92:95]
	v_mfma_f32_16x16x32_bf16 v[88:91], v[160:163], v[200:203], v[88:91]
	v_mfma_f32_16x16x32_bf16 v[88:91], v[164:167], v[204:207], v[88:91]
	v_mfma_f32_16x16x32_bf16 v[76:79], v[140:143], v[208:211], v[76:79]
	v_mfma_f32_16x16x32_bf16 v[76:79], v[156:159], v[212:215], v[76:79]
	v_mfma_f32_16x16x32_bf16 v[72:75], v[160:163], v[208:211], v[72:75]
	v_mfma_f32_16x16x32_bf16 v[72:75], v[164:167], v[212:215], v[72:75]
	s_setprio 0
	s_setprio 2
	v_mfma_f32_16x16x32_bf16 v[116:119], v[168:171], v[184:187], v[116:119]
	v_mfma_f32_16x16x32_bf16 v[116:119], v[172:175], v[188:191], v[116:119]
	v_mfma_f32_16x16x32_bf16 v[112:115], v[176:179], v[184:187], v[112:115]
	v_mfma_f32_16x16x32_bf16 v[112:115], v[180:183], v[188:191], v[112:115]
	v_mfma_f32_16x16x32_bf16 v[100:103], v[168:171], v[192:195], v[100:103]
	v_mfma_f32_16x16x32_bf16 v[100:103], v[172:175], v[196:199], v[100:103]
	v_mfma_f32_16x16x32_bf16 v[96:99], v[176:179], v[192:195], v[96:99]
	v_mfma_f32_16x16x32_bf16 v[96:99], v[180:183], v[196:199], v[96:99]
	v_mfma_f32_16x16x32_bf16 v[84:87], v[168:171], v[200:203], v[84:87]
	v_mfma_f32_16x16x32_bf16 v[84:87], v[172:175], v[204:207], v[84:87]
	v_mfma_f32_16x16x32_bf16 v[80:83], v[176:179], v[200:203], v[80:83]
	v_mfma_f32_16x16x32_bf16 v[80:83], v[180:183], v[204:207], v[80:83]
	v_mfma_f32_16x16x32_bf16 v[68:71], v[168:171], v[208:211], v[68:71]
	v_mfma_f32_16x16x32_bf16 v[68:71], v[172:175], v[212:215], v[68:71]
	s_setprio 3
	s_barrier
	v_mfma_f32_16x16x32_bf16 v[64:67], v[176:179], v[208:211], v[64:67]
	v_mfma_f32_16x16x32_bf16 v[64:67], v[180:183], v[212:215], v[64:67]
	s_setprio 0
	s_add_i32 s51, s41, s25
	s_mov_b32 m0, s51
	ds_read_b128 v[184:187], v151 offset:16384
	ds_read_b128 v[188:191], v250 offset:16384
	ds_read_b128 v[192:195], v151 offset:18432
	ds_read_b128 v[196:199], v250 offset:18432
	ds_read_b128 v[200:203], v151 offset:20480
	ds_read_b128 v[204:207], v250 offset:20480
	global_load_lds_dwordx4 v128, s[16:17]
	s_add_i32 m0, s51, 0x2000
	s_add_u32 s52, s16, 0x404000
	s_addc_u32 s53, s17, 0
	s_add_i32 s51, s42, s25
	global_load_lds_dwordx4 v130, s[16:17]
	s_mov_b32 m0, s51
	ds_read_b128 v[208:211], v151 offset:22528
	global_load_lds_dwordx4 v128, s[52:53]
	s_add_i32 m0, s51, 0x2000
	ds_read_b128 v[212:215], v250 offset:22528
	global_load_lds_dwordx4 v130, s[52:53]
	s_waitcnt vmcnt(6)
	s_waitcnt lgkmcnt(0)
	s_setprio 2
	s_barrier
	v_mfma_f32_16x16x32_bf16 v[60:63], v[140:143], v[184:187], v[60:63]
	v_mfma_f32_16x16x32_bf16 v[60:63], v[156:159], v[188:191], v[60:63]
	v_mfma_f32_16x16x32_bf16 v[56:59], v[160:163], v[184:187], v[56:59]
	v_mfma_f32_16x16x32_bf16 v[56:59], v[164:167], v[188:191], v[56:59]
	v_mfma_f32_16x16x32_bf16 v[44:47], v[140:143], v[192:195], v[44:47]
	v_mfma_f32_16x16x32_bf16 v[44:47], v[156:159], v[196:199], v[44:47]
	v_mfma_f32_16x16x32_bf16 v[40:43], v[160:163], v[192:195], v[40:43]
	v_mfma_f32_16x16x32_bf16 v[40:43], v[164:167], v[196:199], v[40:43]
	v_mfma_f32_16x16x32_bf16 v[28:31], v[140:143], v[200:203], v[28:31]
	v_mfma_f32_16x16x32_bf16 v[28:31], v[156:159], v[204:207], v[28:31]
	v_mfma_f32_16x16x32_bf16 v[24:27], v[160:163], v[200:203], v[24:27]
	v_mfma_f32_16x16x32_bf16 v[24:27], v[164:167], v[204:207], v[24:27]
	v_mfma_f32_16x16x32_bf16 v[12:15], v[140:143], v[208:211], v[12:15]
	v_mfma_f32_16x16x32_bf16 v[12:15], v[156:159], v[212:215], v[12:15]
	v_mfma_f32_16x16x32_bf16 v[8:11], v[160:163], v[208:211], v[8:11]
	v_mfma_f32_16x16x32_bf16 v[8:11], v[164:167], v[212:215], v[8:11]
	s_setprio 0
	s_setprio 2
	v_mfma_f32_16x16x32_bf16 v[52:55], v[168:171], v[184:187], v[52:55]
	v_mfma_f32_16x16x32_bf16 v[52:55], v[172:175], v[188:191], v[52:55]
	v_mfma_f32_16x16x32_bf16 v[48:51], v[176:179], v[184:187], v[48:51]
	v_mfma_f32_16x16x32_bf16 v[48:51], v[180:183], v[188:191], v[48:51]
	v_mfma_f32_16x16x32_bf16 v[36:39], v[168:171], v[192:195], v[36:39]
	v_mfma_f32_16x16x32_bf16 v[36:39], v[172:175], v[196:199], v[36:39]
	v_mfma_f32_16x16x32_bf16 v[32:35], v[176:179], v[192:195], v[32:35]
	v_mfma_f32_16x16x32_bf16 v[32:35], v[180:183], v[196:199], v[32:35]
	v_mfma_f32_16x16x32_bf16 v[20:23], v[168:171], v[200:203], v[20:23]
	v_mfma_f32_16x16x32_bf16 v[20:23], v[172:175], v[204:207], v[20:23]
	v_mfma_f32_16x16x32_bf16 v[16:19], v[176:179], v[200:203], v[16:19]
	v_mfma_f32_16x16x32_bf16 v[16:19], v[180:183], v[204:207], v[16:19]
	v_mfma_f32_16x16x32_bf16 v[4:7], v[168:171], v[208:211], v[4:7]
	v_mfma_f32_16x16x32_bf16 v[4:7], v[172:175], v[212:215], v[4:7]
	s_setprio 3
	s_barrier
; #define PG8_STAGE(bufoff, gbase, voff) do { _Pragma("unroll") for (int _i = 0; _i < 2; ++_i) \
;         __builtin_amdgcn_global_load_lds((const unsigned*)((const char*)(gbase) + (voff)[_i]), (LAS unsigned*)(lds + (bufoff) + ldsw + _i * 8192), 16, 0, 0); } while (0)
; #define PG8_LDA(dst, b, h) do { _Pragma("unroll") for (int m = 0; m < 4; ++m) _Pragma("unroll") for (int k = 0; k < 2; ++k) dst[m][k] = *(const LAS bf16x8*)(lds + PG8_SA(b, h) + aoff + m * 2048 + k * 1024); } while (0)
; #define PG8_LDB(dst, b, h) do { _Pragma("unroll") for (int n = 0; n < 2; ++n) _Pragma("unroll") for (int k = 0; k < 2; ++k) dst[n][k] = *(const LAS bf16x8*)(lds + PG8_SB(b, h) + boff + n * 2048 + k * 1024); } while (0)
; #define PG8_MMA(ai, bj, At, Bt) do { __builtin_amdgcn_s_setprio(3); _Pragma("unroll") for (int m = 0; m < 4; ++m) _Pragma("unroll") for (int n = 0; n < 2; ++n) _Pragma("unroll") for (int k = 0; k < 2; ++k) \
;         acc[ai][bj][m][n] = __builtin_amdgcn_mfma_f32_16x16x32_bf16(Bt[n][k], At[m][k], acc[ai][bj][m][n], 0, 0, 0); __builtin_amdgcn_s_setprio(0); } while (0)
; #define PG8_WAIT_V(n) asm volatile("s_waitcnt vmcnt(" #n ")" ::: "memory")
; #define PG8_WAIT_L(n) asm volatile("s_waitcnt lgkmcnt(" #n ")" ::: "memory")
; #define PG8_BAR __builtin_amdgcn_s_barrier()
; #define PG8_SCHED __builtin_amdgcn_sched_barrier(0)
; template <class Epi, class Sched, bool ALIGN_EPI = false, bool SP2 = false>
; __device__ __forceinline__ void gemm_phase(LAS unsigned char* lds, const Gemm g, const Sched& S, const Epi& E) {
;     ...
;             PG8_LDB(B0, 1, 0); PG8_LDB(B1, 1, 1); PG8_SCHED; PG8_LDA(At, 1, 0); PG8_STAGE(PG8_SA(0, 1), a2 + hsA, voffA);
;             PG8_WAIT_V(8); PG8_WAIT_L(0); PG8_BAR; PG8_MMA(0, 0, At, B0); PG8_MMA(0, 1, At, B1); PG8_BAR; PG8_SCHED;
;             PG8_LDA(At, 1, 1); PG8_STAGE(PG8_SB(1, 0), b3, voffB); PG8_STAGE(PG8_SB(1, 1), b3 + hsB, voffB); PG8_STAGE(PG8_SA(1, 0), a3, voffA);
;             PG8_WAIT_V(8); PG8_WAIT_L(0); PG8_BAR; PG8_MMA(1, 0, At, B0); PG8_MMA(1, 1, At, B1); PG8_BAR; PG8_SCHED;
	v_mfma_f32_16x16x32_bf16 v[0:3], v[176:179], v[208:211], v[0:3]
	v_mfma_f32_16x16x32_bf16 v[0:3], v[180:183], v[212:215], v[0:3]
	s_setprio 0
	s_add_i32 s51, 0, 0x18000
	s_add_i32 s52, 0, 0x1c000
	ds_read_b128 v[140:143], v246
	ds_read_b128 v[156:159], v247
	ds_read_b128 v[160:163], v246 offset:2048
	ds_read_b128 v[164:167], v247 offset:2048
	ds_read_b128 v[168:171], v248
	ds_read_b128 v[172:175], v249
	ds_read_b128 v[176:179], v248 offset:2048
	ds_read_b128 v[180:183], v249 offset:2048
	s_mov_b32 m0, s26
	ds_read_b128 v[204:207], v250 offset:36864
	global_load_lds_dwordx4 v128, s[20:21]
	s_mov_b32 m0, s27
	ds_read_b128 v[208:211], v151 offset:38912
	global_load_lds_dwordx4 v130, s[20:21]
	s_add_u32 s20, s20, 0x404000
	s_addc_u32 s21, s21, 0
	s_mov_b32 m0, s30
	ds_read_b128 v[184:187], v151 offset:32768
	ds_read_b128 v[188:191], v250 offset:32768
	ds_read_b128 v[192:195], v151 offset:34816
	ds_read_b128 v[196:199], v250 offset:34816
	ds_read_b128 v[200:203], v151 offset:36864
	global_load_lds_dwordx4 v128, s[20:21]
	s_mov_b32 m0, s31
	ds_read_b128 v[212:215], v250 offset:38912
	global_load_lds_dwordx4 v130, s[20:21]
	s_waitcnt vmcnt(8)
	s_waitcnt lgkmcnt(0)
	s_setprio 2
	s_barrier
	v_mfma_f32_16x16x32_bf16 v[124:127], v[140:143], v[184:187], v[124:127]
	v_mfma_f32_16x16x32_bf16 v[124:127], v[156:159], v[188:191], v[124:127]
	v_mfma_f32_16x16x32_bf16 v[120:123], v[160:163], v[184:187], v[120:123]
	v_mfma_f32_16x16x32_bf16 v[120:123], v[164:167], v[188:191], v[120:123]
	v_mfma_f32_16x16x32_bf16 v[108:111], v[140:143], v[192:195], v[108:111]
	v_mfma_f32_16x16x32_bf16 v[108:111], v[156:159], v[196:199], v[108:111]
	v_mfma_f32_16x16x32_bf16 v[104:107], v[160:163], v[192:195], v[104:107]
	v_mfma_f32_16x16x32_bf16 v[104:107], v[164:167], v[196:199], v[104:107]
	v_mfma_f32_16x16x32_bf16 v[92:95], v[140:143], v[200:203], v[92:95]
	v_mfma_f32_16x16x32_bf16 v[92:95], v[156:159], v[204:207], v[92:95]
	v_mfma_f32_16x16x32_bf16 v[88:91], v[160:163], v[200:203], v[88:91]
	v_mfma_f32_16x16x32_bf16 v[88:91], v[164:167], v[204:207], v[88:91]
	v_mfma_f32_16x16x32_bf16 v[76:79], v[140:143], v[208:211], v[76:79]
	v_mfma_f32_16x16x32_bf16 v[76:79], v[156:159], v[212:215], v[76:79]
	v_mfma_f32_16x16x32_bf16 v[72:75], v[160:163], v[208:211], v[72:75]
	v_mfma_f32_16x16x32_bf16 v[72:75], v[164:167], v[212:215], v[72:75]
	s_setprio 0
	s_setprio 2
	v_mfma_f32_16x16x32_bf16 v[116:119], v[168:171], v[184:187], v[116:119]
	v_mfma_f32_16x16x32_bf16 v[116:119], v[172:175], v[188:191], v[116:119]
	v_mfma_f32_16x16x32_bf16 v[112:115], v[176:179], v[184:187], v[112:115]
	v_mfma_f32_16x16x32_bf16 v[112:115], v[180:183], v[188:191], v[112:115]
	v_mfma_f32_16x16x32_bf16 v[100:103], v[168:171], v[192:195], v[100:103]
	v_mfma_f32_16x16x32_bf16 v[100:103], v[172:175], v[196:199], v[100:103]
	v_mfma_f32_16x16x32_bf16 v[96:99], v[176:179], v[192:195], v[96:99]
	v_mfma_f32_16x16x32_bf16 v[96:99], v[180:183], v[196:199], v[96:99]
	v_mfma_f32_16x16x32_bf16 v[84:87], v[168:171], v[200:203], v[84:87]
	v_mfma_f32_16x16x32_bf16 v[84:87], v[172:175], v[204:207], v[84:87]
	v_mfma_f32_16x16x32_bf16 v[80:83], v[176:179], v[200:203], v[80:83]
	v_mfma_f32_16x16x32_bf16 v[80:83], v[180:183], v[204:207], v[80:83]
	v_mfma_f32_16x16x32_bf16 v[68:71], v[168:171], v[208:211], v[68:71]
	v_mfma_f32_16x16x32_bf16 v[68:71], v[172:175], v[212:215], v[68:71]
	s_setprio 3
	s_barrier
	v_mfma_f32_16x16x32_bf16 v[64:67], v[176:179], v[208:211], v[64:67]
	v_mfma_f32_16x16x32_bf16 v[64:67], v[180:183], v[212:215], v[64:67]
	s_setprio 0
	s_add_i32 s20, s51, s25
	s_add_u32 s100, s16, s8
	s_addc_u32 s101, s17, s9
	s_mov_b32 m0, s20
	ds_read_b128 v[184:187], v151 offset:49152
	ds_read_b128 v[188:191], v250 offset:49152
	ds_read_b128 v[192:195], v151 offset:51200
	ds_read_b128 v[196:199], v250 offset:51200
	ds_read_b128 v[200:203], v151 offset:53248
	ds_read_b128 v[204:207], v250 offset:53248
	global_load_lds_dwordx4 v128, s[100:101]
	s_add_i32 m0, s20, 0x2000
	s_add_u32 s16, s16, 0x404080
	s_addc_u32 s17, s17, 0
	s_add_i32 s20, s52, s25
	global_load_lds_dwordx4 v130, s[100:101]
	s_mov_b32 m0, s20
	ds_read_b128 v[208:211], v151 offset:55296
	global_load_lds_dwordx4 v128, s[16:17]
	s_add_i32 m0, s20, 0x2000
	ds_read_b128 v[212:215], v250 offset:55296
	global_load_lds_dwordx4 v130, s[16:17]
	s_waitcnt vmcnt(6)
	s_waitcnt lgkmcnt(0)
	s_setprio 2
	s_barrier
	v_mfma_f32_16x16x32_bf16 v[60:63], v[140:143], v[184:187], v[60:63]
	v_mfma_f32_16x16x32_bf16 v[60:63], v[156:159], v[188:191], v[60:63]
	v_mfma_f32_16x16x32_bf16 v[56:59], v[160:163], v[184:187], v[56:59]
	v_mfma_f32_16x16x32_bf16 v[56:59], v[164:167], v[188:191], v[56:59]
	v_mfma_f32_16x16x32_bf16 v[44:47], v[140:143], v[192:195], v[44:47]
	v_mfma_f32_16x16x32_bf16 v[44:47], v[156:159], v[196:199], v[44:47]
	v_mfma_f32_16x16x32_bf16 v[40:43], v[160:163], v[192:195], v[40:43]
	v_mfma_f32_16x16x32_bf16 v[40:43], v[164:167], v[196:199], v[40:43]
	v_mfma_f32_16x16x32_bf16 v[28:31], v[140:143], v[200:203], v[28:31]
	v_mfma_f32_16x16x32_bf16 v[28:31], v[156:159], v[204:207], v[28:31]
	v_mfma_f32_16x16x32_bf16 v[24:27], v[160:163], v[200:203], v[24:27]
	v_mfma_f32_16x16x32_bf16 v[24:27], v[164:167], v[204:207], v[24:27]
	v_mfma_f32_16x16x32_bf16 v[12:15], v[140:143], v[208:211], v[12:15]
	v_mfma_f32_16x16x32_bf16 v[12:15], v[156:159], v[212:215], v[12:15]
	v_mfma_f32_16x16x32_bf16 v[8:11], v[160:163], v[208:211], v[8:11]
	v_mfma_f32_16x16x32_bf16 v[8:11], v[164:167], v[212:215], v[8:11]
	s_setprio 0
	s_setprio 2
	v_mfma_f32_16x16x32_bf16 v[52:55], v[168:171], v[184:187], v[52:55]
	v_mfma_f32_16x16x32_bf16 v[52:55], v[172:175], v[188:191], v[52:55]
	v_mfma_f32_16x16x32_bf16 v[48:51], v[176:179], v[184:187], v[48:51]
	v_mfma_f32_16x16x32_bf16 v[48:51], v[180:183], v[188:191], v[48:51]
	v_mfma_f32_16x16x32_bf16 v[36:39], v[168:171], v[192:195], v[36:39]
	v_mfma_f32_16x16x32_bf16 v[36:39], v[172:175], v[196:199], v[36:39]
	v_mfma_f32_16x16x32_bf16 v[32:35], v[176:179], v[192:195], v[32:35]
	v_mfma_f32_16x16x32_bf16 v[32:35], v[180:183], v[196:199], v[32:35]
	v_mfma_f32_16x16x32_bf16 v[20:23], v[168:171], v[200:203], v[20:23]
	v_mfma_f32_16x16x32_bf16 v[20:23], v[172:175], v[204:207], v[20:23]
	v_mfma_f32_16x16x32_bf16 v[16:19], v[176:179], v[200:203], v[16:19]
	v_mfma_f32_16x16x32_bf16 v[16:19], v[180:183], v[204:207], v[16:19]
	v_mfma_f32_16x16x32_bf16 v[4:7], v[168:171], v[208:211], v[4:7]
	v_mfma_f32_16x16x32_bf16 v[4:7], v[172:175], v[212:215], v[4:7]
	s_setprio 3
	s_barrier
	v_mfma_f32_16x16x32_bf16 v[0:3], v[176:179], v[208:211], v[0:3]
	v_mfma_f32_16x16x32_bf16 v[0:3], v[180:183], v[212:215], v[0:3]
	s_setprio 0
	s_add_i32 s50, s50, 2
	s_add_u32 s14, s14, 0x100
	s_addc_u32 s15, s15, 0
	s_add_u32 s48, s48, 0x100
	s_addc_u32 s49, s49, 0
	s_cmpk_gt_u32 s50, 0xfd
	s_cbranch_scc0 .LBB0_350
	s_and_b64 vcc, exec, s[10:11]
	s_cbranch_vccz .LBB0_353
	s_barrier
